# v28 + DYN GEMM publish: no cross-XCD ticket stealing (7 serialized returning atomics inside the K-loop) when all 8 XCDs have resident workgroups
# baseline (speedup 1.0000x reference)
; #define PG8_STAGE(bufoff, gbase, voff) do { _Pragma("unroll") for (int _i = 0; _i < 2; ++_i) \
;         __builtin_amdgcn_global_load_lds((const unsigned*)((const char*)(gbase) + (voff)[_i]), (LAS unsigned*)(lds + (bufoff) + ldsw + _i * 8192), 16, 0, 0); } while (0)
; #define PG8_LDA(dst, b, h) do { _Pragma("unroll") for (int m = 0; m < 4; ++m) _Pragma("unroll") for (int k = 0; k < 2; ++k) dst[m][k] = *(const LAS bf16x8*)(lds + PG8_SA(b, h) + aoff + m * 2048 + k * 1024); } while (0)
; #define PG8_LDB(dst, b, h) do { _Pragma("unroll") for (int n = 0; n < 2; ++n) _Pragma("unroll") for (int k = 0; k < 2; ++k) dst[n][k] = *(const LAS bf16x8*)(lds + PG8_SB(b, h) + boff + n * 2048 + k * 1024); } while (0)
; #define PG8_WAIT_L(n) asm volatile("s_waitcnt lgkmcnt(" #n ")" ::: "memory")
; template <class Epi, bool DYN = false>
; __device__ __forceinline__ void gemm_phase(LAS unsigned char* lds, const Gemm g, const Epi& E, int wave, unsigned* ctr = nullptr) {
;     ...
;         bool has_next = DYN ? false : S.next(ui + 1, nxt);
;         const char* nA = has_next ? (const char*)(g.A + (size_t)nxt.b * g.sA) + (size_t)nxt.pm * tstepA : cA; const char* nB = has_next ? (const char*)(g.Bt + (size_t)nxt.b * g.sB) + (size_t)nxt.pn * tstepB : cB;
;         for (int t = 0; t < nt; t += 2) {
;             const bool last = (t == nt - 2);
;             if (DYN && last) { const int nw = __builtin_amdgcn_readfirstlane(slot[(ui + 1) & 1]); has_next = nw >= 0;
;                 if (has_next) { decode(nw, nxt); nA = (const char*)g.A + (size_t)nxt.pm * tstepA; nB = (const char*)g.Bt + (size_t)nxt.pn * tstepB; } }
;             const char* a1 = cA + (size_t)(t + 1) * kstepA;
;             const char* a2 = last ? nA : cA + (size_t)(t + 2) * kstepA; const char* b2 = last ? nB : cB + (size_t)(t + 2) * kstepB;
;             const char* a3 = a2 + kstepA; const char* b3 = b2 + kstepB;
;             PG8_LDB(B0, 0, 0); PG8_SCHED; PG8_LDA(At, 0, 0); PG8_STAGE(PG8_SA(1, 1), a1 + hstepA, voffA);
;             PG8_WAIT_L(8); PG8_BAR; PG8_WAIT_L(0); PG8_MMA(0, 0, At, B0); PG8_BAR; PG8_SCHED;
;             PG8_LDB(B1, 0, 1); PG8_STAGE(PG8_SB(0, 0), b2, voffB);
;             PG8_BAR; PG8_WAIT_L(0); PG8_MMA(0, 1, At, B1); PG8_BAR;
;             PG8_LDA(At, 0, 1); PG8_STAGE(PG8_SA(0, 0), a2, voffA);
;             PG8_BAR; PG8_WAIT_L(0); PG8_MMA(1, 0, At, B0); PG8_BAR; PG8_SCHED;
.LBB0_86:
	s_add_i32 s8, s8, 2
	s_add_u32 s9, s68, s72
	s_addc_u32 s10, s69, s73
	s_and_b64 s[0:1], s[38:39], exec
	s_cselect_b32 s75, s79, s10
	s_cselect_b32 s74, s78, s9
	s_add_i32 s9, 0, 0x10000
	v_add_u32_e32 v142, s9, v200
	ds_read_b128 v[130:133], v142
	ds_read_b128 v[134:137], v142 offset:1024
	ds_read_b128 v[138:141], v142 offset:2048
	ds_read_b128 v[142:145], v142 offset:3072
	s_and_b64 s[0:1], s[38:39], exec
	s_cselect_b32 s71, s65, s7
	s_cselect_b32 s70, s64, s6
	v_lshl_add_u64 v[196:197], s[68:69], 0, v[188:189]
	s_add_i32 m0, s18, 0xc000
	ds_read_b128 v[146:149], v202
	ds_read_b128 v[150:153], v202 offset:1024
	ds_read_b128 v[154:157], v202 offset:2048
	ds_read_b128 v[158:161], v202 offset:3072
	ds_read_b128 v[162:165], v202 offset:4096
	ds_read_b128 v[166:169], v202 offset:5120
	ds_read_b128 v[170:173], v202 offset:6144
	ds_read_b128 v[174:177], v202 offset:7168
	global_load_lds_dwordx4 v[196:197], off
	v_lshl_add_u64 v[196:197], s[68:69], 0, v[190:191]
	s_add_i32 m0, s18, 0xe000
	s_nop 0
	global_load_lds_dwordx4 v[196:197], off
	s_waitcnt lgkmcnt(8)
	s_barrier
	s_waitcnt lgkmcnt(0)
	s_setprio 1
	s_waitcnt lgkmcnt(0)
	v_mfma_f32_16x16x32_bf16 v[126:129], v[130:133], v[146:149], v[126:129]
	v_mfma_f32_16x16x32_bf16 v[122:125], v[138:141], v[146:149], v[122:125]
	v_mfma_f32_16x16x32_bf16 v[118:121], v[130:133], v[154:157], v[118:121]
	v_mfma_f32_16x16x32_bf16 v[114:117], v[138:141], v[154:157], v[114:117]
	v_mfma_f32_16x16x32_bf16 v[110:113], v[130:133], v[162:165], v[110:113]
	v_mfma_f32_16x16x32_bf16 v[106:109], v[138:141], v[162:165], v[106:109]
	v_mfma_f32_16x16x32_bf16 v[102:105], v[130:133], v[170:173], v[102:105]
	v_mfma_f32_16x16x32_bf16 v[94:97], v[138:141], v[170:173], v[94:97]
	v_mfma_f32_16x16x32_bf16 v[126:129], v[134:137], v[150:153], v[126:129]
	v_mfma_f32_16x16x32_bf16 v[122:125], v[142:145], v[150:153], v[122:125]
	v_mfma_f32_16x16x32_bf16 v[118:121], v[134:137], v[158:161], v[118:121]
	v_mfma_f32_16x16x32_bf16 v[114:117], v[142:145], v[158:161], v[114:117]
	v_mfma_f32_16x16x32_bf16 v[110:113], v[134:137], v[166:169], v[110:113]
	v_mfma_f32_16x16x32_bf16 v[106:109], v[142:145], v[166:169], v[106:109]
	v_mfma_f32_16x16x32_bf16 v[102:105], v[134:137], v[174:177], v[102:105]
	v_mfma_f32_16x16x32_bf16 v[94:97], v[142:145], v[174:177], v[94:97]
	s_setprio 0
	s_barrier
	s_add_i32 s10, 0, 0x14000
	s_add_i32 s0, s9, s17
	v_add_u32_e32 v212, s10, v200
	v_lshl_add_u64 v[216:217], s[70:71], 0, v[178:179]
	s_mov_b32 m0, s0
	ds_read_b128 v[196:199], v212
	ds_read_b128 v[204:207], v212 offset:1024
	ds_read_b128 v[208:211], v212 offset:2048
	ds_read_b128 v[212:215], v212 offset:3072
	global_load_lds_dwordx4 v[216:217], off
	v_lshl_add_u64 v[216:217], s[70:71], 0, v[182:183]
	s_add_i32 m0, s0, 0x2000
	s_nop 0
	global_load_lds_dwordx4 v[216:217], off
	s_barrier
	s_waitcnt lgkmcnt(0)
	s_setprio 1
	s_waitcnt lgkmcnt(0)
	v_mfma_f32_16x16x32_bf16 v[86:89], v[196:199], v[146:149], v[86:89]
	v_mfma_f32_16x16x32_bf16 v[78:81], v[208:211], v[146:149], v[78:81]
	v_mfma_f32_16x16x32_bf16 v[70:73], v[196:199], v[154:157], v[70:73]
	v_mfma_f32_16x16x32_bf16 v[62:65], v[208:211], v[154:157], v[62:65]
	v_mfma_f32_16x16x32_bf16 v[54:57], v[196:199], v[162:165], v[54:57]
	v_mfma_f32_16x16x32_bf16 v[46:49], v[208:211], v[162:165], v[46:49]
	v_mfma_f32_16x16x32_bf16 v[42:45], v[196:199], v[170:173], v[42:45]
	v_mfma_f32_16x16x32_bf16 v[38:41], v[208:211], v[170:173], v[38:41]
	v_mfma_f32_16x16x32_bf16 v[86:89], v[204:207], v[150:153], v[86:89]
	v_mfma_f32_16x16x32_bf16 v[78:81], v[212:215], v[150:153], v[78:81]
	v_mfma_f32_16x16x32_bf16 v[70:73], v[204:207], v[158:161], v[70:73]
	v_mfma_f32_16x16x32_bf16 v[62:65], v[212:215], v[158:161], v[62:65]
	v_mfma_f32_16x16x32_bf16 v[54:57], v[204:207], v[166:169], v[54:57]
	v_mfma_f32_16x16x32_bf16 v[46:49], v[212:215], v[166:169], v[46:49]
	v_mfma_f32_16x16x32_bf16 v[42:45], v[204:207], v[174:177], v[42:45]
	v_mfma_f32_16x16x32_bf16 v[38:41], v[212:215], v[174:177], v[38:41]
	s_setprio 0
	s_mov_b32 m0, s18
	v_lshl_add_u64 v[216:217], s[74:75], 0, v[0:1]
	s_barrier
	ds_read_b128 v[146:149], v202 offset:16384
	ds_read_b128 v[150:153], v202 offset:17408
	ds_read_b128 v[154:157], v202 offset:18432
	ds_read_b128 v[158:161], v202 offset:19456
	ds_read_b128 v[162:165], v202 offset:20480
	ds_read_b128 v[166:169], v202 offset:21504
	ds_read_b128 v[170:173], v202 offset:22528
	ds_read_b128 v[174:177], v202 offset:23552
	global_load_lds_dwordx4 v[216:217], off
	v_lshl_add_u64 v[218:219], s[74:75], 0, v[180:181]
	s_mov_b32 m0, s19
	s_nop 0
	global_load_lds_dwordx4 v[218:219], off
	s_barrier
	s_waitcnt lgkmcnt(0)
	s_setprio 1
	s_waitcnt lgkmcnt(0)
	v_mfma_f32_16x16x32_bf16 v[34:37], v[130:133], v[146:149], v[34:37]
	v_mfma_f32_16x16x32_bf16 v[26:29], v[138:141], v[146:149], v[26:29]
	v_mfma_f32_16x16x32_bf16 v[22:25], v[130:133], v[154:157], v[22:25]
	v_mfma_f32_16x16x32_bf16 v[18:21], v[138:141], v[154:157], v[18:21]
	v_mfma_f32_16x16x32_bf16 v[14:17], v[130:133], v[162:165], v[14:17]
	v_mfma_f32_16x16x32_bf16 v[10:13], v[138:141], v[162:165], v[10:13]
	v_mfma_f32_16x16x32_bf16 v[6:9], v[130:133], v[170:173], v[6:9]
	v_mfma_f32_16x16x32_bf16 v[2:5], v[138:141], v[170:173], v[2:5]
	v_mfma_f32_16x16x32_bf16 v[34:37], v[134:137], v[150:153], v[34:37]
	v_mfma_f32_16x16x32_bf16 v[26:29], v[142:145], v[150:153], v[26:29]
	v_mfma_f32_16x16x32_bf16 v[22:25], v[134:137], v[158:161], v[22:25]
	v_mfma_f32_16x16x32_bf16 v[18:21], v[142:145], v[158:161], v[18:21]
	v_mfma_f32_16x16x32_bf16 v[14:17], v[134:137], v[166:169], v[14:17]
	v_mfma_f32_16x16x32_bf16 v[10:13], v[142:145], v[166:169], v[10:13]
	v_mfma_f32_16x16x32_bf16 v[6:9], v[134:137], v[174:177], v[6:9]
	v_mfma_f32_16x16x32_bf16 v[2:5], v[142:145], v[174:177], v[2:5]
	s_setprio 0
	s_barrier
; #define PG8_STAGE(bufoff, gbase, voff) do { _Pragma("unroll") for (int _i = 0; _i < 2; ++_i) \
;         __builtin_amdgcn_global_load_lds((const unsigned*)((const char*)(gbase) + (voff)[_i]), (LAS unsigned*)(lds + (bufoff) + ldsw + _i * 8192), 16, 0, 0); } while (0)
; #define PG8_LDA(dst, b, h) do { _Pragma("unroll") for (int m = 0; m < 4; ++m) _Pragma("unroll") for (int k = 0; k < 2; ++k) dst[m][k] = *(const LAS bf16x8*)(lds + PG8_SA(b, h) + aoff + m * 2048 + k * 1024); } while (0)
; #define PG8_LDB(dst, b, h) do { _Pragma("unroll") for (int n = 0; n < 2; ++n) _Pragma("unroll") for (int k = 0; k < 2; ++k) dst[n][k] = *(const LAS bf16x8*)(lds + PG8_SB(b, h) + boff + n * 2048 + k * 1024); } while (0)
; #define PG8_MMA(ai, bj, At, Bt) do { __builtin_amdgcn_s_setprio(1); _Pragma("unroll") for (int m = 0; m < 4; ++m) _Pragma("unroll") for (int n = 0; n < 2; ++n) _Pragma("unroll") for (int k = 0; k < 2; ++k) \
;         acc[ai][bj][m][n] = __builtin_amdgcn_mfma_f32_16x16x32_bf16(Bt[n][k], At[m][k], acc[ai][bj][m][n], 0, 0, 0); __builtin_amdgcn_s_setprio(0); } while (0)
; #define PG8_WAIT_V(n) asm volatile("s_waitcnt vmcnt(" #n ")" ::: "memory")
; #define PG8_WAIT_L(n) asm volatile("s_waitcnt lgkmcnt(" #n ")" ::: "memory")
; #define PG8_BAR __builtin_amdgcn_s_barrier()
; #define PG8_SCHED __builtin_amdgcn_sched_barrier(0)
; template <class Epi, bool DYN = false>
; __device__ __forceinline__ void gemm_phase(LAS unsigned char* lds, const Gemm g, const Epi& E, int wave, unsigned* ctr = nullptr) {
;     ...
;             PG8_STAGE(PG8_SB(0, 1), b2 + hstepB, voffB);
;             PG8_WAIT_V(6); PG8_BAR; PG8_MMA(1, 1, At, B1); PG8_BAR;
;             PG8_LDB(B0, 1, 0); PG8_SCHED; PG8_LDA(At, 1, 0); PG8_STAGE(PG8_SA(0, 1), a2 + hstepA, voffA);
;             PG8_WAIT_L(8); PG8_BAR; PG8_WAIT_L(0); PG8_MMA(0, 0, At, B0); PG8_BAR; PG8_SCHED;
;             PG8_LDB(B1, 1, 1); PG8_STAGE(PG8_SB(1, 0), b3, voffB);
;             PG8_BAR; PG8_WAIT_L(0); PG8_MMA(0, 1, At, B1); PG8_BAR;
	s_add_u32 s0, s70, 0x4000
	s_addc_u32 s1, s71, 0
	s_add_i32 s9, s10, s17
	v_lshl_add_u64 v[130:131], s[0:1], 0, v[178:179]
	s_mov_b32 m0, s9
	s_nop 0
	global_load_lds_dwordx4 v[130:131], off
	v_lshl_add_u64 v[130:131], s[0:1], 0, v[182:183]
	s_add_i32 m0, s9, 0x2000
	s_nop 0
	global_load_lds_dwordx4 v[130:131], off
	s_waitcnt vmcnt(6)
	s_barrier
	s_setprio 1
	v_mfma_f32_16x16x32_bf16 v[98:101], v[196:199], v[146:149], v[98:101]
	v_mfma_f32_16x16x32_bf16 v[90:93], v[208:211], v[146:149], v[90:93]
	v_mfma_f32_16x16x32_bf16 v[82:85], v[196:199], v[154:157], v[82:85]
	v_mfma_f32_16x16x32_bf16 v[74:77], v[208:211], v[154:157], v[74:77]
	v_mfma_f32_16x16x32_bf16 v[66:69], v[196:199], v[162:165], v[66:69]
	v_mfma_f32_16x16x32_bf16 v[58:61], v[208:211], v[162:165], v[58:61]
	v_mfma_f32_16x16x32_bf16 v[50:53], v[196:199], v[170:173], v[50:53]
	v_mfma_f32_16x16x32_bf16 v[30:33], v[208:211], v[170:173], v[30:33]
	v_mfma_f32_16x16x32_bf16 v[98:101], v[204:207], v[150:153], v[98:101]
	v_mfma_f32_16x16x32_bf16 v[90:93], v[212:215], v[150:153], v[90:93]
	v_mfma_f32_16x16x32_bf16 v[82:85], v[204:207], v[158:161], v[82:85]
	v_mfma_f32_16x16x32_bf16 v[74:77], v[212:215], v[158:161], v[74:77]
	v_mfma_f32_16x16x32_bf16 v[66:69], v[204:207], v[166:169], v[66:69]
	v_mfma_f32_16x16x32_bf16 v[58:61], v[212:215], v[166:169], v[58:61]
	v_mfma_f32_16x16x32_bf16 v[50:53], v[204:207], v[174:177], v[50:53]
	v_mfma_f32_16x16x32_bf16 v[30:33], v[212:215], v[174:177], v[30:33]
	s_setprio 0
	s_add_i32 s9, 0, 0x18000
	v_add_u32_e32 v130, s9, v200
	s_barrier
	ds_read_b128 v[196:199], v130
	ds_read_b128 v[204:207], v130 offset:1024
	ds_read_b128 v[208:211], v130 offset:2048
	ds_read_b128 v[212:215], v130 offset:3072
	s_add_u32 s0, s74, 0x80000
	s_addc_u32 s1, s75, 0
	s_mov_b32 m0, s28
	v_lshl_add_u64 v[130:131], s[0:1], 0, v[0:1]
	ds_read_b128 v[146:149], v202 offset:32768
	ds_read_b128 v[150:153], v202 offset:33792
	ds_read_b128 v[154:157], v202 offset:34816
	ds_read_b128 v[158:161], v202 offset:35840
	ds_read_b128 v[162:165], v202 offset:36864
	ds_read_b128 v[166:169], v202 offset:37888
	ds_read_b128 v[170:173], v202 offset:38912
	ds_read_b128 v[174:177], v202 offset:39936
	global_load_lds_dwordx4 v[130:131], off
	v_lshl_add_u64 v[130:131], s[0:1], 0, v[180:181]
	s_mov_b32 m0, s33
	s_nop 0
	global_load_lds_dwordx4 v[130:131], off
	s_waitcnt lgkmcnt(8)
	s_barrier
	s_waitcnt lgkmcnt(0)
	s_setprio 1
	s_waitcnt lgkmcnt(0)
	v_mfma_f32_16x16x32_bf16 v[126:129], v[196:199], v[146:149], v[126:129]
	v_mfma_f32_16x16x32_bf16 v[122:125], v[208:211], v[146:149], v[122:125]
	v_mfma_f32_16x16x32_bf16 v[118:121], v[196:199], v[154:157], v[118:121]
	v_mfma_f32_16x16x32_bf16 v[114:117], v[208:211], v[154:157], v[114:117]
	v_mfma_f32_16x16x32_bf16 v[110:113], v[196:199], v[162:165], v[110:113]
	v_mfma_f32_16x16x32_bf16 v[106:109], v[208:211], v[162:165], v[106:109]
	v_mfma_f32_16x16x32_bf16 v[102:105], v[196:199], v[170:173], v[102:105]
	v_mfma_f32_16x16x32_bf16 v[94:97], v[208:211], v[170:173], v[94:97]
	v_mfma_f32_16x16x32_bf16 v[126:129], v[204:207], v[150:153], v[126:129]
	v_mfma_f32_16x16x32_bf16 v[122:125], v[212:215], v[150:153], v[122:125]
	v_mfma_f32_16x16x32_bf16 v[118:121], v[204:207], v[158:161], v[118:121]
	v_mfma_f32_16x16x32_bf16 v[114:117], v[212:215], v[158:161], v[114:117]
	v_mfma_f32_16x16x32_bf16 v[110:113], v[204:207], v[166:169], v[110:113]
	v_mfma_f32_16x16x32_bf16 v[106:109], v[212:215], v[166:169], v[106:109]
	v_mfma_f32_16x16x32_bf16 v[102:105], v[204:207], v[174:177], v[102:105]
	v_mfma_f32_16x16x32_bf16 v[94:97], v[212:215], v[174:177], v[94:97]
	s_setprio 0
	s_barrier
	s_add_u32 s0, s70, 0x8000
	v_add_u32_e32 v130, 0, v200
	s_addc_u32 s1, s71, 0
	s_add_i32 s9, s9, s17
	v_add_u32_e32 v142, 0x1c000, v130
	v_lshl_add_u64 v[220:221], s[0:1], 0, v[178:179]
	s_mov_b32 m0, s9
	ds_read_b128 v[130:133], v142
	ds_read_b128 v[134:137], v142 offset:1024
	ds_read_b128 v[138:141], v142 offset:2048
	ds_read_b128 v[142:145], v142 offset:3072
	global_load_lds_dwordx4 v[220:221], off
	v_lshl_add_u64 v[220:221], s[0:1], 0, v[182:183]
	s_add_i32 m0, s9, 0x2000
	s_nop 0
	global_load_lds_dwordx4 v[220:221], off
	s_barrier
	s_waitcnt lgkmcnt(0)
	s_setprio 1
	s_waitcnt lgkmcnt(0)
	v_mfma_f32_16x16x32_bf16 v[86:89], v[130:133], v[146:149], v[86:89]
	v_mfma_f32_16x16x32_bf16 v[78:81], v[138:141], v[146:149], v[78:81]
	v_mfma_f32_16x16x32_bf16 v[70:73], v[130:133], v[154:157], v[70:73]
	v_mfma_f32_16x16x32_bf16 v[62:65], v[138:141], v[154:157], v[62:65]
	v_mfma_f32_16x16x32_bf16 v[54:57], v[130:133], v[162:165], v[54:57]
	v_mfma_f32_16x16x32_bf16 v[46:49], v[138:141], v[162:165], v[46:49]
	v_mfma_f32_16x16x32_bf16 v[42:45], v[130:133], v[170:173], v[42:45]
	v_mfma_f32_16x16x32_bf16 v[38:41], v[138:141], v[170:173], v[38:41]
	v_mfma_f32_16x16x32_bf16 v[86:89], v[134:137], v[150:153], v[86:89]
	v_mfma_f32_16x16x32_bf16 v[78:81], v[142:145], v[150:153], v[78:81]
	v_mfma_f32_16x16x32_bf16 v[70:73], v[134:137], v[158:161], v[70:73]
	v_mfma_f32_16x16x32_bf16 v[62:65], v[142:145], v[158:161], v[62:65]
	v_mfma_f32_16x16x32_bf16 v[54:57], v[134:137], v[166:169], v[54:57]
	v_mfma_f32_16x16x32_bf16 v[46:49], v[142:145], v[166:169], v[46:49]
	v_mfma_f32_16x16x32_bf16 v[42:45], v[134:137], v[174:177], v[42:45]
	v_mfma_f32_16x16x32_bf16 v[38:41], v[142:145], v[174:177], v[38:41]
	s_setprio 0
	s_mov_b32 m0, s41
	v_lshl_add_u64 v[216:217], v[216:217], 0, s[52:53]
	s_barrier
; #define PG8_STAGE(bufoff, gbase, voff) do { _Pragma("unroll") for (int _i = 0; _i < 2; ++_i) \
;         __builtin_amdgcn_global_load_lds((const unsigned*)((const char*)(gbase) + (voff)[_i]), (LAS unsigned*)(lds + (bufoff) + ldsw + _i * 8192), 16, 0, 0); } while (0)
; #define PG8_LDA(dst, b, h) do { _Pragma("unroll") for (int m = 0; m < 4; ++m) _Pragma("unroll") for (int k = 0; k < 2; ++k) dst[m][k] = *(const LAS bf16x8*)(lds + PG8_SA(b, h) + aoff + m * 2048 + k * 1024); } while (0)
; #define PG8_MMA(ai, bj, At, Bt) do { __builtin_amdgcn_s_setprio(1); _Pragma("unroll") for (int m = 0; m < 4; ++m) _Pragma("unroll") for (int n = 0; n < 2; ++n) _Pragma("unroll") for (int k = 0; k < 2; ++k) \
;         acc[ai][bj][m][n] = __builtin_amdgcn_mfma_f32_16x16x32_bf16(Bt[n][k], At[m][k], acc[ai][bj][m][n], 0, 0, 0); __builtin_amdgcn_s_setprio(0); } while (0)
; #define PG8_WAIT_L(n) asm volatile("s_waitcnt lgkmcnt(" #n ")" ::: "memory")
; #define PG8_BAR __builtin_amdgcn_s_barrier()
; #define PG8_SCHED __builtin_amdgcn_sched_barrier(0)
; template <class Epi, bool DYN = false>
; __device__ __forceinline__ void gemm_phase(LAS unsigned char* lds, const Gemm g, const Epi& E, int wave, unsigned* ctr = nullptr) {
;     ...
;     auto publish = [&](int si) { if (tid == 0) { int wg = -1;
;             if (ticket < rng_cnt(xcd)) wg = rng_start(xcd) + ticket;
;             else { for (int k = 1; k < 8; ++k) { const int x2 = (xcd + k) & 7; const int t2 = (int)__hip_atomic_fetch_add(ctr + x2 * 16, 1u, __ATOMIC_RELAXED, __HIP_MEMORY_SCOPE_AGENT); if (t2 < rng_cnt(x2)) { wg = rng_start(x2) + t2; break; } } }
;             slot[si] = wg; } };
;     ...
;             PG8_BAR; PG8_WAIT_L(0); PG8_MMA(0, 1, At, B1); PG8_BAR;
;             PG8_LDA(At, 1, 1); PG8_STAGE(PG8_SA(1, 0), a3, voffA);
;             PG8_BAR; PG8_WAIT_L(0); PG8_MMA(1, 0, At, B0); PG8_BAR; PG8_SCHED;
;             if (DYN && t == 0) publish((ui + 1) & 1);
	ds_read_b128 v[170:173], v202 offset:49152
	ds_read_b128 v[174:177], v202 offset:50176
	ds_read_b128 v[162:165], v202 offset:51200
	ds_read_b128 v[166:169], v202 offset:52224
	ds_read_b128 v[154:157], v202 offset:53248
	ds_read_b128 v[158:161], v202 offset:54272
	ds_read_b128 v[146:149], v202 offset:55296
	ds_read_b128 v[150:153], v202 offset:56320
	global_load_lds_dwordx4 v[216:217], off
	v_lshl_add_u64 v[216:217], v[218:219], 0, s[52:53]
	s_mov_b32 m0, s43
	s_nop 0
	global_load_lds_dwordx4 v[216:217], off
	s_barrier
	s_waitcnt lgkmcnt(0)
	s_setprio 1
	s_waitcnt lgkmcnt(0)
	v_mfma_f32_16x16x32_bf16 v[34:37], v[196:199], v[170:173], v[34:37]
	v_mfma_f32_16x16x32_bf16 v[26:29], v[208:211], v[170:173], v[26:29]
	v_mfma_f32_16x16x32_bf16 v[22:25], v[196:199], v[162:165], v[22:25]
	v_mfma_f32_16x16x32_bf16 v[18:21], v[208:211], v[162:165], v[18:21]
	v_mfma_f32_16x16x32_bf16 v[14:17], v[196:199], v[154:157], v[14:17]
	v_mfma_f32_16x16x32_bf16 v[10:13], v[208:211], v[154:157], v[10:13]
	v_mfma_f32_16x16x32_bf16 v[6:9], v[196:199], v[146:149], v[6:9]
	v_mfma_f32_16x16x32_bf16 v[2:5], v[208:211], v[146:149], v[2:5]
	v_mfma_f32_16x16x32_bf16 v[34:37], v[204:207], v[174:177], v[34:37]
	v_mfma_f32_16x16x32_bf16 v[26:29], v[212:215], v[174:177], v[26:29]
	v_mfma_f32_16x16x32_bf16 v[22:25], v[204:207], v[166:169], v[22:25]
	v_mfma_f32_16x16x32_bf16 v[18:21], v[212:215], v[166:169], v[18:21]
	v_mfma_f32_16x16x32_bf16 v[14:17], v[204:207], v[158:161], v[14:17]
	v_mfma_f32_16x16x32_bf16 v[10:13], v[212:215], v[158:161], v[10:13]
	v_mfma_f32_16x16x32_bf16 v[6:9], v[204:207], v[150:153], v[6:9]
	v_mfma_f32_16x16x32_bf16 v[2:5], v[212:215], v[150:153], v[2:5]
	s_setprio 0
	s_barrier
	v_or_b32_e32 v196, s8, v192
	v_cmp_eq_u32_e64 s[38:39], 0, v196
	s_and_saveexec_b64 s[74:75], s[38:39]
	s_cbranch_execz .LBB0_81
	v_cmp_lt_i32_e32 vcc, s91, v193
	v_add_u32_e32 v203, s23, v193
	v_mov_b32_e32 v204, v203
	s_and_saveexec_b64 s[36:37], vcc
	s_cbranch_execz .LBB0_80
	v_readlane_b32 s0, v254, 11
	s_nop 1
	v_mov_b32_e32 v196, s0
	ds_read_b32 v196, v196
	v_mov_b32_e32 v204, -1
	s_waitcnt lgkmcnt(0)
	v_readfirstlane_b32 s0, v196
	s_cmp_eq_u32 s0, 8
	s_cbranch_scc1 .LBB0_80
	v_mov_b64_e32 v[196:197], s[44:45]
	s_waitcnt vmcnt(0)
	flat_atomic_add v196, v[196:197], v224 sc0
	s_waitcnt vmcnt(0) lgkmcnt(0)
	v_cmp_lt_i32_e64 s[38:39], s91, v196
	v_add_u32_e32 v204, s2, v196
	s_and_saveexec_b64 s[0:1], s[38:39]
	s_cbranch_execz .LBB0_79
	v_mov_b64_e32 v[196:197], s[58:59]
	flat_atomic_add v196, v[196:197], v224 sc0
	s_waitcnt vmcnt(0) lgkmcnt(0)
	v_cmp_lt_i32_e64 s[38:39], s91, v196
	v_add_u32_e32 v204, s66, v196
	s_and_saveexec_b64 s[80:81], s[38:39]
	s_cbranch_execz .LBB0_78
	v_mov_b64_e32 v[196:197], s[60:61]
	flat_atomic_add v196, v[196:197], v224 sc0
	s_movk_i32 s9, 0x60
	s_waitcnt vmcnt(0) lgkmcnt(0)
	v_cmp_lt_i32_e64 s[38:39], s91, v196
	v_add_u32_e32 v204, s67, v196
	s_and_saveexec_b64 s[82:83], s[38:39]
	s_cbranch_execz .LBB0_77
	v_mov_b64_e32 v[196:197], s[62:63]
	flat_atomic_add v196, v[196:197], v224 sc0
	s_waitcnt vmcnt(0) lgkmcnt(0)
	v_cmp_lt_i32_e64 s[38:39], s91, v196
	v_add_u32_e32 v204, s22, v196
	s_and_saveexec_b64 s[84:85], s[38:39]
	s_cbranch_execz .LBB0_76
	v_mov_b64_e32 v[196:197], s[92:93]
	flat_atomic_add v196, v[196:197], v224 sc0
	v_readlane_b32 s10, v255, 2
	s_waitcnt vmcnt(0) lgkmcnt(0)
	v_cmp_lt_i32_e64 s[38:39], s91, v196
	v_add_u32_e32 v204, s10, v196
	s_and_saveexec_b64 s[86:87], s[38:39]
	s_cbranch_execz .LBB0_75
	v_readlane_b32 s38, v255, 4
	v_readlane_b32 s39, v255, 5
	v_readlane_b32 s10, v255, 6
	s_nop 0
	v_mov_b64_e32 v[196:197], s[38:39]
	flat_atomic_add v196, v[196:197], v224 sc0
	s_waitcnt vmcnt(0) lgkmcnt(0)
	v_cmp_lt_i32_e64 s[38:39], s91, v196
	v_add_u32_e32 v204, s10, v196
	s_and_saveexec_b64 s[88:89], s[38:39]
	s_cbranch_execz .LBB0_74
	v_readlane_b32 s38, v255, 8
	v_readlane_b32 s39, v255, 9
	v_readlane_b32 s10, v255, 10
	s_nop 0
	v_mov_b64_e32 v[196:197], s[38:39]
	flat_atomic_add v196, v[196:197], v224 sc0
	s_waitcnt vmcnt(0) lgkmcnt(0)
	v_add_u32_e32 v197, s10, v196
	v_cmp_gt_i32_e64 s[38:39], s9, v196
	s_nop 1
	v_cndmask_b32_e64 v204, -1, v197, s[38:39]
	s_branch .LBB0_74

; #define PG8_STAGE(bufoff, gbase, voff) do { _Pragma("unroll") for (int _i = 0; _i < 2; ++_i) \
;         __builtin_amdgcn_global_load_lds((const unsigned*)((const char*)(gbase) + (voff)[_i]), (LAS unsigned*)(lds + (bufoff) + ldsw + _i * 8192), 16, 0, 0); } while (0)
; #define PG8_LDA(dst, b, h) do { _Pragma("unroll") for (int m = 0; m < 4; ++m) _Pragma("unroll") for (int k = 0; k < 2; ++k) dst[m][k] = *(const LAS bf16x8*)(lds + PG8_SA(b, h) + aoff + m * 2048 + k * 1024); } while (0)
; #define PG8_LDB(dst, b, h) do { _Pragma("unroll") for (int n = 0; n < 2; ++n) _Pragma("unroll") for (int k = 0; k < 2; ++k) dst[n][k] = *(const LAS bf16x8*)(lds + PG8_SB(b, h) + boff + n * 2048 + k * 1024); } while (0)
; #define PG8_MMA(ai, bj, At, Bt) do { __builtin_amdgcn_s_setprio(1); _Pragma("unroll") for (int m = 0; m < 4; ++m) _Pragma("unroll") for (int n = 0; n < 2; ++n) _Pragma("unroll") for (int k = 0; k < 2; ++k) \
;         acc[ai][bj][m][n] = __builtin_amdgcn_mfma_f32_16x16x32_bf16(Bt[n][k], At[m][k], acc[ai][bj][m][n], 0, 0, 0); __builtin_amdgcn_s_setprio(0); } while (0)
; template <class Epi, bool DYN = false>
; __device__ __forceinline__ void gemm_phase(LAS unsigned char* lds, const Gemm g, const Epi& E, int wave, unsigned* ctr = nullptr) {
;     ...
;         for (int t = 0; t < nt; t += 2) {
;             const bool last = (t == nt - 2);
;             if (DYN && last) { const int nw = __builtin_amdgcn_readfirstlane(slot[(ui + 1) & 1]); has_next = nw >= 0;
;                 if (has_next) { decode(nw, nxt); nA = (const char*)g.A + (size_t)nxt.pm * tstepA; nB = (const char*)g.Bt + (size_t)nxt.pn * tstepB; } }
;             const char* a1 = cA + (size_t)(t + 1) * kstepA;
;             const char* a2 = last ? nA : cA + (size_t)(t + 2) * kstepA; const char* b2 = last ? nB : cB + (size_t)(t + 2) * kstepB;
;             const char* a3 = a2 + kstepA; const char* b3 = b2 + kstepB;
;             PG8_LDB(B0, 0, 0); PG8_SCHED; PG8_LDA(At, 0, 0); PG8_STAGE(PG8_SA(1, 1), a1 + hstepA, voffA);
;             PG8_WAIT_L(8); PG8_BAR; PG8_WAIT_L(0); PG8_MMA(0, 0, At, B0); PG8_BAR; PG8_SCHED;
;             PG8_LDB(B1, 0, 1); PG8_STAGE(PG8_SB(0, 0), b2, voffB);
;             PG8_BAR; PG8_WAIT_L(0); PG8_MMA(0, 1, At, B1); PG8_BAR;
;             PG8_LDA(At, 0, 1); PG8_STAGE(PG8_SA(0, 0), a2, voffA);
;             PG8_BAR; PG8_WAIT_L(0); PG8_MMA(1, 0, At, B0); PG8_BAR; PG8_SCHED;
.LBB0_510:
	s_add_i32 s3, s3, 2
	s_add_u32 s0, s74, s40
	s_addc_u32 s1, s75, s41
	s_add_u32 s4, s0, 0x10000
	s_addc_u32 s5, s1, 0
	s_and_b64 s[0:1], s[36:37], exec
	s_cselect_b32 s43, s77, s5
	s_cselect_b32 s42, s76, s4
	s_add_u32 s4, s19, s40
	s_addc_u32 s5, s15, s41
	s_add_u32 s38, s42, 0x8000
	s_addc_u32 s39, s43, 0
	s_add_i32 s6, 0, 0x10000
	v_add_u32_e32 v142, s6, v201
	ds_read_b128 v[130:133], v142
	ds_read_b128 v[134:137], v142 offset:1024
	ds_read_b128 v[138:141], v142 offset:2048
	ds_read_b128 v[142:145], v142 offset:3072
	s_and_b64 s[0:1], s[36:37], exec
	s_cselect_b32 s37, s67, s5
	s_cselect_b32 s36, s66, s4
	v_lshl_add_u64 v[196:197], v[210:211], 0, s[40:41]
	s_add_i32 m0, s45, 0xc000
	ds_read_b128 v[146:149], v212
	ds_read_b128 v[150:153], v212 offset:1024
	ds_read_b128 v[154:157], v212 offset:2048
	ds_read_b128 v[158:161], v212 offset:3072
	ds_read_b128 v[162:165], v212 offset:4096
	ds_read_b128 v[166:169], v212 offset:5120
	ds_read_b128 v[170:173], v212 offset:6144
	ds_read_b128 v[174:177], v212 offset:7168
	global_load_lds_dwordx4 v[196:197], off
	v_lshl_add_u64 v[196:197], v[208:209], 0, s[40:41]
	s_add_i32 m0, s45, 0xe000
	s_nop 0
	global_load_lds_dwordx4 v[196:197], off
	s_waitcnt lgkmcnt(8)
	s_barrier
	s_waitcnt lgkmcnt(0)
	s_setprio 1
	s_waitcnt lgkmcnt(0)
	v_mfma_f32_16x16x32_bf16 v[2:5], v[130:133], v[146:149], v[2:5]
	v_mfma_f32_16x16x32_bf16 v[30:33], v[138:141], v[146:149], v[30:33]
	v_mfma_f32_16x16x32_bf16 v[26:29], v[130:133], v[154:157], v[26:29]
	v_mfma_f32_16x16x32_bf16 v[22:25], v[138:141], v[154:157], v[22:25]
	v_mfma_f32_16x16x32_bf16 v[18:21], v[130:133], v[162:165], v[18:21]
	v_mfma_f32_16x16x32_bf16 v[14:17], v[138:141], v[162:165], v[14:17]
	v_mfma_f32_16x16x32_bf16 v[10:13], v[130:133], v[170:173], v[10:13]
	v_mfma_f32_16x16x32_bf16 v[6:9], v[138:141], v[170:173], v[6:9]
	v_mfma_f32_16x16x32_bf16 v[2:5], v[134:137], v[150:153], v[2:5]
	v_mfma_f32_16x16x32_bf16 v[30:33], v[142:145], v[150:153], v[30:33]
	v_mfma_f32_16x16x32_bf16 v[26:29], v[134:137], v[158:161], v[26:29]
	v_mfma_f32_16x16x32_bf16 v[22:25], v[142:145], v[158:161], v[22:25]
	v_mfma_f32_16x16x32_bf16 v[18:21], v[134:137], v[166:169], v[18:21]
	v_mfma_f32_16x16x32_bf16 v[14:17], v[142:145], v[166:169], v[14:17]
	v_mfma_f32_16x16x32_bf16 v[10:13], v[134:137], v[174:177], v[10:13]
	v_mfma_f32_16x16x32_bf16 v[6:9], v[142:145], v[174:177], v[6:9]
	s_setprio 0
	s_barrier
	s_add_i32 s4, 0, 0x14000
	s_add_i32 s0, s6, s81
	v_add_u32_e32 v232, s4, v201
	v_lshl_add_u64 v[244:245], s[36:37], 0, v[0:1]
	s_mov_b32 m0, s0
	ds_read_b128 v[196:199], v232
	ds_read_b128 v[214:217], v232 offset:1024
	ds_read_b128 v[218:221], v232 offset:2048
	ds_read_b128 v[232:235], v232 offset:3072
	global_load_lds_dwordx4 v[244:245], off
	v_lshl_add_u64 v[244:245], s[36:37], 0, v[182:183]
	s_add_i32 m0, s0, 0x2000
	s_nop 0
	global_load_lds_dwordx4 v[244:245], off
	s_barrier
	s_waitcnt lgkmcnt(0)
	s_setprio 1
	s_waitcnt lgkmcnt(0)
	v_mfma_f32_16x16x32_bf16 v[94:97], v[196:199], v[146:149], v[94:97]
	v_mfma_f32_16x16x32_bf16 v[90:93], v[218:221], v[146:149], v[90:93]
	v_mfma_f32_16x16x32_bf16 v[86:89], v[196:199], v[154:157], v[86:89]
	v_mfma_f32_16x16x32_bf16 v[82:85], v[218:221], v[154:157], v[82:85]
	v_mfma_f32_16x16x32_bf16 v[78:81], v[196:199], v[162:165], v[78:81]
	v_mfma_f32_16x16x32_bf16 v[74:77], v[218:221], v[162:165], v[74:77]
	v_mfma_f32_16x16x32_bf16 v[70:73], v[196:199], v[170:173], v[70:73]
	v_mfma_f32_16x16x32_bf16 v[66:69], v[218:221], v[170:173], v[66:69]
	v_mfma_f32_16x16x32_bf16 v[94:97], v[214:217], v[150:153], v[94:97]
	v_mfma_f32_16x16x32_bf16 v[90:93], v[232:235], v[150:153], v[90:93]
	v_mfma_f32_16x16x32_bf16 v[86:89], v[214:217], v[158:161], v[86:89]
	v_mfma_f32_16x16x32_bf16 v[82:85], v[232:235], v[158:161], v[82:85]
	v_mfma_f32_16x16x32_bf16 v[78:81], v[214:217], v[166:169], v[78:81]
	v_mfma_f32_16x16x32_bf16 v[74:77], v[232:235], v[166:169], v[74:77]
	v_mfma_f32_16x16x32_bf16 v[70:73], v[214:217], v[174:177], v[70:73]
	v_mfma_f32_16x16x32_bf16 v[66:69], v[232:235], v[174:177], v[66:69]
	s_setprio 0
	s_mov_b32 m0, s45
	v_lshl_add_u64 v[244:245], s[42:43], 0, v[178:179]
	s_barrier
	ds_read_b128 v[146:149], v212 offset:16384
	ds_read_b128 v[150:153], v212 offset:17408
	ds_read_b128 v[154:157], v212 offset:18432
	ds_read_b128 v[158:161], v212 offset:19456
	ds_read_b128 v[162:165], v212 offset:20480
	ds_read_b128 v[166:169], v212 offset:21504
	ds_read_b128 v[170:173], v212 offset:22528
	ds_read_b128 v[174:177], v212 offset:23552
	global_load_lds_dwordx4 v[244:245], off
	v_lshl_add_u64 v[244:245], s[42:43], 0, v[180:181]
	s_mov_b32 m0, s83
	s_nop 0
	global_load_lds_dwordx4 v[244:245], off
	s_barrier
	s_waitcnt lgkmcnt(0)
	s_setprio 1
	s_waitcnt lgkmcnt(0)
	v_mfma_f32_16x16x32_bf16 v[62:65], v[130:133], v[146:149], v[62:65]
	v_mfma_f32_16x16x32_bf16 v[58:61], v[138:141], v[146:149], v[58:61]
	v_mfma_f32_16x16x32_bf16 v[54:57], v[130:133], v[154:157], v[54:57]
	v_mfma_f32_16x16x32_bf16 v[50:53], v[138:141], v[154:157], v[50:53]
	v_mfma_f32_16x16x32_bf16 v[46:49], v[130:133], v[162:165], v[46:49]
	v_mfma_f32_16x16x32_bf16 v[42:45], v[138:141], v[162:165], v[42:45]
	v_mfma_f32_16x16x32_bf16 v[38:41], v[130:133], v[170:173], v[38:41]
	v_mfma_f32_16x16x32_bf16 v[34:37], v[138:141], v[170:173], v[34:37]
	v_mfma_f32_16x16x32_bf16 v[62:65], v[134:137], v[150:153], v[62:65]
	v_mfma_f32_16x16x32_bf16 v[58:61], v[142:145], v[150:153], v[58:61]
	v_mfma_f32_16x16x32_bf16 v[54:57], v[134:137], v[158:161], v[54:57]
	v_mfma_f32_16x16x32_bf16 v[50:53], v[142:145], v[158:161], v[50:53]
	v_mfma_f32_16x16x32_bf16 v[46:49], v[134:137], v[166:169], v[46:49]
	v_mfma_f32_16x16x32_bf16 v[42:45], v[142:145], v[166:169], v[42:45]
	v_mfma_f32_16x16x32_bf16 v[38:41], v[134:137], v[174:177], v[38:41]
	v_mfma_f32_16x16x32_bf16 v[34:37], v[142:145], v[174:177], v[34:37]
	s_setprio 0
	s_barrier
; #define PG8_STAGE(bufoff, gbase, voff) do { _Pragma("unroll") for (int _i = 0; _i < 2; ++_i) \
;         __builtin_amdgcn_global_load_lds((const unsigned*)((const char*)(gbase) + (voff)[_i]), (LAS unsigned*)(lds + (bufoff) + ldsw + _i * 8192), 16, 0, 0); } while (0)
; #define PG8_LDA(dst, b, h) do { _Pragma("unroll") for (int m = 0; m < 4; ++m) _Pragma("unroll") for (int k = 0; k < 2; ++k) dst[m][k] = *(const LAS bf16x8*)(lds + PG8_SA(b, h) + aoff + m * 2048 + k * 1024); } while (0)
; #define PG8_LDB(dst, b, h) do { _Pragma("unroll") for (int n = 0; n < 2; ++n) _Pragma("unroll") for (int k = 0; k < 2; ++k) dst[n][k] = *(const LAS bf16x8*)(lds + PG8_SB(b, h) + boff + n * 2048 + k * 1024); } while (0)
; #define PG8_MMA(ai, bj, At, Bt) do { __builtin_amdgcn_s_setprio(1); _Pragma("unroll") for (int m = 0; m < 4; ++m) _Pragma("unroll") for (int n = 0; n < 2; ++n) _Pragma("unroll") for (int k = 0; k < 2; ++k) \
;         acc[ai][bj][m][n] = __builtin_amdgcn_mfma_f32_16x16x32_bf16(Bt[n][k], At[m][k], acc[ai][bj][m][n], 0, 0, 0); __builtin_amdgcn_s_setprio(0); } while (0)
; #define PG8_WAIT_V(n) asm volatile("s_waitcnt vmcnt(" #n ")" ::: "memory")
; #define PG8_WAIT_L(n) asm volatile("s_waitcnt lgkmcnt(" #n ")" ::: "memory")
; #define PG8_BAR __builtin_amdgcn_s_barrier()
; #define PG8_SCHED __builtin_amdgcn_sched_barrier(0)
; template <class Epi, bool DYN = false>
; __device__ __forceinline__ void gemm_phase(LAS unsigned char* lds, const Gemm g, const Epi& E, int wave, unsigned* ctr = nullptr) {
;     ...
;             PG8_STAGE(PG8_SB(0, 1), b2 + hstepB, voffB);
;             PG8_WAIT_V(6); PG8_BAR; PG8_MMA(1, 1, At, B1); PG8_BAR;
;             PG8_LDB(B0, 1, 0); PG8_SCHED; PG8_LDA(At, 1, 0); PG8_STAGE(PG8_SA(0, 1), a2 + hstepA, voffA);
;             PG8_WAIT_L(8); PG8_BAR; PG8_WAIT_L(0); PG8_MMA(0, 0, At, B0); PG8_BAR; PG8_SCHED;
;             PG8_LDB(B1, 1, 1); PG8_STAGE(PG8_SB(1, 0), b3, voffB);
;             PG8_BAR; PG8_WAIT_L(0); PG8_MMA(0, 1, At, B1); PG8_BAR;
	s_add_u32 s0, s36, 0x4000
	s_addc_u32 s1, s37, 0
	s_add_i32 s4, s4, s81
	v_lshl_add_u64 v[130:131], s[0:1], 0, v[0:1]
	s_mov_b32 m0, s4
	s_nop 0
	global_load_lds_dwordx4 v[130:131], off
	v_lshl_add_u64 v[130:131], s[0:1], 0, v[182:183]
	s_add_i32 m0, s4, 0x2000
	s_nop 0
	global_load_lds_dwordx4 v[130:131], off
	s_waitcnt vmcnt(6)
	s_barrier
	s_setprio 1
	v_mfma_f32_16x16x32_bf16 v[126:129], v[196:199], v[146:149], v[126:129]
	v_mfma_f32_16x16x32_bf16 v[122:125], v[218:221], v[146:149], v[122:125]
	v_mfma_f32_16x16x32_bf16 v[118:121], v[196:199], v[154:157], v[118:121]
	v_mfma_f32_16x16x32_bf16 v[114:117], v[218:221], v[154:157], v[114:117]
	v_mfma_f32_16x16x32_bf16 v[110:113], v[196:199], v[162:165], v[110:113]
	v_mfma_f32_16x16x32_bf16 v[106:109], v[218:221], v[162:165], v[106:109]
	v_mfma_f32_16x16x32_bf16 v[102:105], v[196:199], v[170:173], v[102:105]
	v_mfma_f32_16x16x32_bf16 v[98:101], v[218:221], v[170:173], v[98:101]
	v_mfma_f32_16x16x32_bf16 v[126:129], v[214:217], v[150:153], v[126:129]
	v_mfma_f32_16x16x32_bf16 v[122:125], v[232:235], v[150:153], v[122:125]
	v_mfma_f32_16x16x32_bf16 v[118:121], v[214:217], v[158:161], v[118:121]
	v_mfma_f32_16x16x32_bf16 v[114:117], v[232:235], v[158:161], v[114:117]
	v_mfma_f32_16x16x32_bf16 v[110:113], v[214:217], v[166:169], v[110:113]
	v_mfma_f32_16x16x32_bf16 v[106:109], v[232:235], v[166:169], v[106:109]
	v_mfma_f32_16x16x32_bf16 v[102:105], v[214:217], v[174:177], v[102:105]
	v_mfma_f32_16x16x32_bf16 v[98:101], v[232:235], v[174:177], v[98:101]
	s_setprio 0
	s_add_i32 s4, 0, 0x18000
	v_add_u32_e32 v130, s4, v201
	s_barrier
	ds_read_b128 v[196:199], v130
	ds_read_b128 v[214:217], v130 offset:1024
	ds_read_b128 v[218:221], v130 offset:2048
	ds_read_b128 v[232:235], v130 offset:3072
	s_add_u32 s0, s42, 0x4000
	s_addc_u32 s1, s43, 0
	s_mov_b32 m0, s84
	v_lshl_add_u64 v[130:131], s[0:1], 0, v[178:179]
	ds_read_b128 v[146:149], v212 offset:32768
	ds_read_b128 v[150:153], v212 offset:33792
	ds_read_b128 v[154:157], v212 offset:34816
	ds_read_b128 v[158:161], v212 offset:35840
	ds_read_b128 v[162:165], v212 offset:36864
	ds_read_b128 v[166:169], v212 offset:37888
	ds_read_b128 v[170:173], v212 offset:38912
	ds_read_b128 v[174:177], v212 offset:39936
	global_load_lds_dwordx4 v[130:131], off
	v_lshl_add_u64 v[130:131], s[0:1], 0, v[180:181]
	s_mov_b32 m0, s85
	s_nop 0
	global_load_lds_dwordx4 v[130:131], off
	s_waitcnt lgkmcnt(8)
	s_barrier
	s_waitcnt lgkmcnt(0)
	s_setprio 1
	s_waitcnt lgkmcnt(0)
	v_mfma_f32_16x16x32_bf16 v[2:5], v[196:199], v[146:149], v[2:5]
	v_mfma_f32_16x16x32_bf16 v[30:33], v[218:221], v[146:149], v[30:33]
	v_mfma_f32_16x16x32_bf16 v[26:29], v[196:199], v[154:157], v[26:29]
	v_mfma_f32_16x16x32_bf16 v[22:25], v[218:221], v[154:157], v[22:25]
	v_mfma_f32_16x16x32_bf16 v[18:21], v[196:199], v[162:165], v[18:21]
	v_mfma_f32_16x16x32_bf16 v[14:17], v[218:221], v[162:165], v[14:17]
	v_mfma_f32_16x16x32_bf16 v[10:13], v[196:199], v[170:173], v[10:13]
	v_mfma_f32_16x16x32_bf16 v[6:9], v[218:221], v[170:173], v[6:9]
	v_mfma_f32_16x16x32_bf16 v[2:5], v[214:217], v[150:153], v[2:5]
	v_mfma_f32_16x16x32_bf16 v[30:33], v[232:235], v[150:153], v[30:33]
	v_mfma_f32_16x16x32_bf16 v[26:29], v[214:217], v[158:161], v[26:29]
	v_mfma_f32_16x16x32_bf16 v[22:25], v[232:235], v[158:161], v[22:25]
	v_mfma_f32_16x16x32_bf16 v[18:21], v[214:217], v[166:169], v[18:21]
	v_mfma_f32_16x16x32_bf16 v[14:17], v[232:235], v[166:169], v[14:17]
	v_mfma_f32_16x16x32_bf16 v[10:13], v[214:217], v[174:177], v[10:13]
	v_mfma_f32_16x16x32_bf16 v[6:9], v[232:235], v[174:177], v[6:9]
	s_setprio 0
	s_barrier
	s_add_u32 s0, s36, 0x8000
	v_add_u32_e32 v130, 0, v201
	s_addc_u32 s1, s37, 0
	s_add_i32 s4, s4, s81
	v_add_u32_e32 v142, 0x1c000, v130
	v_lshl_add_u64 v[244:245], s[0:1], 0, v[0:1]
	s_mov_b32 m0, s4
	ds_read_b128 v[130:133], v142
	ds_read_b128 v[134:137], v142 offset:1024
	ds_read_b128 v[138:141], v142 offset:2048
	ds_read_b128 v[142:145], v142 offset:3072
	global_load_lds_dwordx4 v[244:245], off
	v_lshl_add_u64 v[244:245], s[0:1], 0, v[182:183]
	s_add_i32 m0, s4, 0x2000
	s_nop 0
	global_load_lds_dwordx4 v[244:245], off
	s_barrier
	s_waitcnt lgkmcnt(0)
	s_setprio 1
	s_waitcnt lgkmcnt(0)
	v_mfma_f32_16x16x32_bf16 v[94:97], v[130:133], v[146:149], v[94:97]
	v_mfma_f32_16x16x32_bf16 v[90:93], v[138:141], v[146:149], v[90:93]
	v_mfma_f32_16x16x32_bf16 v[86:89], v[130:133], v[154:157], v[86:89]
	v_mfma_f32_16x16x32_bf16 v[82:85], v[138:141], v[154:157], v[82:85]
	v_mfma_f32_16x16x32_bf16 v[78:81], v[130:133], v[162:165], v[78:81]
	v_mfma_f32_16x16x32_bf16 v[74:77], v[138:141], v[162:165], v[74:77]
	v_mfma_f32_16x16x32_bf16 v[70:73], v[130:133], v[170:173], v[70:73]
	v_mfma_f32_16x16x32_bf16 v[66:69], v[138:141], v[170:173], v[66:69]
	v_mfma_f32_16x16x32_bf16 v[94:97], v[134:137], v[150:153], v[94:97]
	v_mfma_f32_16x16x32_bf16 v[90:93], v[142:145], v[150:153], v[90:93]
	v_mfma_f32_16x16x32_bf16 v[86:89], v[134:137], v[158:161], v[86:89]
	v_mfma_f32_16x16x32_bf16 v[82:85], v[142:145], v[158:161], v[82:85]
	v_mfma_f32_16x16x32_bf16 v[78:81], v[134:137], v[166:169], v[78:81]
	v_mfma_f32_16x16x32_bf16 v[74:77], v[142:145], v[166:169], v[74:77]
	v_mfma_f32_16x16x32_bf16 v[70:73], v[134:137], v[174:177], v[70:73]
	v_mfma_f32_16x16x32_bf16 v[66:69], v[142:145], v[174:177], v[66:69]
	s_setprio 0
	s_mov_b32 m0, s86
	v_lshl_add_u64 v[244:245], s[38:39], 0, v[178:179]
	s_barrier
; #define PG8_STAGE(bufoff, gbase, voff) do { _Pragma("unroll") for (int _i = 0; _i < 2; ++_i) \
;         __builtin_amdgcn_global_load_lds((const unsigned*)((const char*)(gbase) + (voff)[_i]), (LAS unsigned*)(lds + (bufoff) + ldsw + _i * 8192), 16, 0, 0); } while (0)
; #define PG8_LDA(dst, b, h) do { _Pragma("unroll") for (int m = 0; m < 4; ++m) _Pragma("unroll") for (int k = 0; k < 2; ++k) dst[m][k] = *(const LAS bf16x8*)(lds + PG8_SA(b, h) + aoff + m * 2048 + k * 1024); } while (0)
; #define PG8_MMA(ai, bj, At, Bt) do { __builtin_amdgcn_s_setprio(1); _Pragma("unroll") for (int m = 0; m < 4; ++m) _Pragma("unroll") for (int n = 0; n < 2; ++n) _Pragma("unroll") for (int k = 0; k < 2; ++k) \
;         acc[ai][bj][m][n] = __builtin_amdgcn_mfma_f32_16x16x32_bf16(Bt[n][k], At[m][k], acc[ai][bj][m][n], 0, 0, 0); __builtin_amdgcn_s_setprio(0); } while (0)
; #define PG8_WAIT_L(n) asm volatile("s_waitcnt lgkmcnt(" #n ")" ::: "memory")
; #define PG8_BAR __builtin_amdgcn_s_barrier()
; #define PG8_SCHED __builtin_amdgcn_sched_barrier(0)
; template <class Epi, bool DYN = false>
; __device__ __forceinline__ void gemm_phase(LAS unsigned char* lds, const Gemm g, const Epi& E, int wave, unsigned* ctr = nullptr) {
;     ...
;     auto publish = [&](int si) { if (tid == 0) { int wg = -1;
;             if (ticket < rng_cnt(xcd)) wg = rng_start(xcd) + ticket;
;             else { for (int k = 1; k < 8; ++k) { const int x2 = (xcd + k) & 7; const int t2 = (int)__hip_atomic_fetch_add(ctr + x2 * 16, 1u, __ATOMIC_RELAXED, __HIP_MEMORY_SCOPE_AGENT); if (t2 < rng_cnt(x2)) { wg = rng_start(x2) + t2; break; } } }
;             slot[si] = wg; } };
;     ...
;             PG8_LDA(At, 1, 1); PG8_STAGE(PG8_SA(1, 0), a3, voffA);
;             PG8_BAR; PG8_WAIT_L(0); PG8_MMA(1, 0, At, B0); PG8_BAR; PG8_SCHED;
;             if (DYN && t == 0) publish((ui + 1) & 1);
	ds_read_b128 v[170:173], v212 offset:49152
	ds_read_b128 v[174:177], v212 offset:50176
	ds_read_b128 v[162:165], v212 offset:51200
	ds_read_b128 v[166:169], v212 offset:52224
	ds_read_b128 v[154:157], v212 offset:53248
	ds_read_b128 v[158:161], v212 offset:54272
	ds_read_b128 v[146:149], v212 offset:55296
	ds_read_b128 v[150:153], v212 offset:56320
	global_load_lds_dwordx4 v[244:245], off
	v_lshl_add_u64 v[244:245], s[38:39], 0, v[180:181]
	s_mov_b32 m0, s87
	s_nop 0
	global_load_lds_dwordx4 v[244:245], off
	s_barrier
	s_waitcnt lgkmcnt(0)
	s_setprio 1
	s_waitcnt lgkmcnt(0)
	v_mfma_f32_16x16x32_bf16 v[62:65], v[196:199], v[170:173], v[62:65]
	v_mfma_f32_16x16x32_bf16 v[58:61], v[218:221], v[170:173], v[58:61]
	v_mfma_f32_16x16x32_bf16 v[54:57], v[196:199], v[162:165], v[54:57]
	v_mfma_f32_16x16x32_bf16 v[50:53], v[218:221], v[162:165], v[50:53]
	v_mfma_f32_16x16x32_bf16 v[46:49], v[196:199], v[154:157], v[46:49]
	v_mfma_f32_16x16x32_bf16 v[42:45], v[218:221], v[154:157], v[42:45]
	v_mfma_f32_16x16x32_bf16 v[38:41], v[196:199], v[146:149], v[38:41]
	v_mfma_f32_16x16x32_bf16 v[34:37], v[218:221], v[146:149], v[34:37]
	v_mfma_f32_16x16x32_bf16 v[62:65], v[214:217], v[174:177], v[62:65]
	v_mfma_f32_16x16x32_bf16 v[58:61], v[232:235], v[174:177], v[58:61]
	v_mfma_f32_16x16x32_bf16 v[54:57], v[214:217], v[166:169], v[54:57]
	v_mfma_f32_16x16x32_bf16 v[50:53], v[232:235], v[166:169], v[50:53]
	v_mfma_f32_16x16x32_bf16 v[46:49], v[214:217], v[158:161], v[46:49]
	v_mfma_f32_16x16x32_bf16 v[42:45], v[232:235], v[158:161], v[42:45]
	v_mfma_f32_16x16x32_bf16 v[38:41], v[214:217], v[150:153], v[38:41]
	v_mfma_f32_16x16x32_bf16 v[34:37], v[232:235], v[150:153], v[34:37]
	s_setprio 0
	s_barrier
	v_or_b32_e32 v196, s3, v187
	v_cmp_eq_u32_e64 s[38:39], 0, v196
	s_and_saveexec_b64 s[42:43], s[38:39]
	s_cbranch_execz .LBB0_505
	v_readlane_b32 s0, v254, 49
	v_cmp_lt_i32_e32 vcc, 0x287, v189
	s_nop 1
	v_add_u32_e32 v213, s0, v189
	v_mov_b32_e32 v214, v213
	s_and_saveexec_b64 s[46:47], vcc
	s_cbranch_execz .LBB0_504
	v_readlane_b32 s0, v254, 11
	s_nop 1
	v_mov_b32_e32 v196, s0
	ds_read_b32 v196, v196
	v_mov_b32_e32 v214, -1
	s_waitcnt lgkmcnt(0)
	v_readfirstlane_b32 s0, v196
	s_cmp_eq_u32 s0, 8
	s_cbranch_scc1 .LBB0_504
	v_mov_b64_e32 v[196:197], s[50:51]
	s_waitcnt vmcnt(0)
	flat_atomic_add v196, v[196:197], v224 sc0
	s_movk_i32 s0, 0x287
	s_waitcnt vmcnt(0) lgkmcnt(0)
	v_cmp_lt_i32_e64 s[38:39], s0, v196
	v_add_u32_e32 v214, s80, v196
	s_and_saveexec_b64 s[0:1], s[38:39]
	s_cbranch_execz .LBB0_503
	v_mov_b64_e32 v[196:197], s[54:55]
	flat_atomic_add v196, v[196:197], v224 sc0
	s_movk_i32 s4, 0x287
	s_waitcnt vmcnt(0) lgkmcnt(0)
	v_cmp_lt_i32_e64 s[38:39], s4, v196
	v_add_u32_e32 v214, s82, v196
	s_and_saveexec_b64 s[60:61], s[38:39]
	s_cbranch_execz .LBB0_502
	v_mov_b64_e32 v[196:197], s[58:59]
	flat_atomic_add v196, v[196:197], v224 sc0
	s_waitcnt vmcnt(0) lgkmcnt(0)
	v_cmp_lt_i32_e64 s[38:39], s4, v196
	v_add_u32_e32 v214, s17, v196
	s_and_saveexec_b64 s[62:63], s[38:39]
	s_cbranch_execz .LBB0_501
	v_mov_b64_e32 v[196:197], s[90:91]
	flat_atomic_add v196, v[196:197], v224 sc0
	s_waitcnt vmcnt(0) lgkmcnt(0)
	v_cmp_lt_i32_e64 s[38:39], s4, v196
	v_add_u32_e32 v214, s23, v196
	s_and_saveexec_b64 s[64:65], s[38:39]
	s_cbranch_execz .LBB0_500
	v_readlane_b32 s4, v255, 0
	v_readlane_b32 s5, v255, 1
	s_nop 1
	v_mov_b64_e32 v[196:197], s[4:5]
	flat_atomic_add v196, v[196:197], v224 sc0
	s_movk_i32 s4, 0x287
	s_waitcnt vmcnt(0) lgkmcnt(0)
	v_cmp_lt_i32_e64 s[38:39], s4, v196
	v_readlane_b32 s4, v255, 2
	s_nop 1
	v_add_u32_e32 v214, s4, v196
	s_and_saveexec_b64 s[68:69], s[38:39]
	s_cbranch_execz .LBB0_499
	v_readlane_b32 s4, v255, 4
	v_readlane_b32 s5, v255, 5
	s_nop 1
	v_mov_b64_e32 v[196:197], s[4:5]
	flat_atomic_add v196, v[196:197], v224 sc0
	s_movk_i32 s4, 0x287
	s_waitcnt vmcnt(0) lgkmcnt(0)
	v_cmp_lt_i32_e64 s[38:39], s4, v196
	v_readlane_b32 s4, v255, 6
	s_nop 1
	v_add_u32_e32 v214, s4, v196
	s_and_saveexec_b64 s[70:71], s[38:39]
	s_cbranch_execz .LBB0_498
	v_readlane_b32 s4, v255, 8
	v_readlane_b32 s5, v255, 9
	s_nop 1
	v_mov_b64_e32 v[196:197], s[4:5]
	flat_atomic_add v196, v[196:197], v224 sc0
	v_readlane_b32 s4, v255, 10
	s_waitcnt vmcnt(0) lgkmcnt(0)
	s_nop 0
	v_add_u32_e32 v197, s4, v196
	s_movk_i32 s4, 0x288
	v_cmp_gt_i32_e64 s[38:39], s4, v196
	s_nop 1
	v_cndmask_b32_e64 v214, -1, v197, s[38:39]
	s_branch .LBB0_498

; #define PG8_STAGE(bufoff, gbase, voff) do { _Pragma("unroll") for (int _i = 0; _i < 2; ++_i) \
;         __builtin_amdgcn_global_load_lds((const unsigned*)((const char*)(gbase) + (voff)[_i]), (LAS unsigned*)(lds + (bufoff) + ldsw + _i * 8192), 16, 0, 0); } while (0)
; #define PG8_LDA(dst, b, h) do { _Pragma("unroll") for (int m = 0; m < 4; ++m) _Pragma("unroll") for (int k = 0; k < 2; ++k) dst[m][k] = *(const LAS bf16x8*)(lds + PG8_SA(b, h) + aoff + m * 2048 + k * 1024); } while (0)
; #define PG8_LDB(dst, b, h) do { _Pragma("unroll") for (int n = 0; n < 2; ++n) _Pragma("unroll") for (int k = 0; k < 2; ++k) dst[n][k] = *(const LAS bf16x8*)(lds + PG8_SB(b, h) + boff + n * 2048 + k * 1024); } while (0)
; #define PG8_MMA(ai, bj, At, Bt) do { __builtin_amdgcn_s_setprio(1); _Pragma("unroll") for (int m = 0; m < 4; ++m) _Pragma("unroll") for (int n = 0; n < 2; ++n) _Pragma("unroll") for (int k = 0; k < 2; ++k) \
;         acc[ai][bj][m][n] = __builtin_amdgcn_mfma_f32_16x16x32_bf16(Bt[n][k], At[m][k], acc[ai][bj][m][n], 0, 0, 0); __builtin_amdgcn_s_setprio(0); } while (0)
; template <class Epi, bool DYN = false>
; __device__ __forceinline__ void gemm_phase(LAS unsigned char* lds, const Gemm g, const Epi& E, int wave, unsigned* ctr = nullptr) {
;     ...
;         for (int t = 0; t < nt; t += 2) {
;             const bool last = (t == nt - 2);
;             if (DYN && last) { const int nw = __builtin_amdgcn_readfirstlane(slot[(ui + 1) & 1]); has_next = nw >= 0;
;                 if (has_next) { decode(nw, nxt); nA = (const char*)g.A + (size_t)nxt.pm * tstepA; nB = (const char*)g.Bt + (size_t)nxt.pn * tstepB; } }
;             const char* a1 = cA + (size_t)(t + 1) * kstepA;
;             const char* a2 = last ? nA : cA + (size_t)(t + 2) * kstepA; const char* b2 = last ? nB : cB + (size_t)(t + 2) * kstepB;
;             const char* a3 = a2 + kstepA; const char* b3 = b2 + kstepB;
;             PG8_LDB(B0, 0, 0); PG8_SCHED; PG8_LDA(At, 0, 0); PG8_STAGE(PG8_SA(1, 1), a1 + hstepA, voffA);
;             PG8_WAIT_L(8); PG8_BAR; PG8_WAIT_L(0); PG8_MMA(0, 0, At, B0); PG8_BAR; PG8_SCHED;
;             PG8_LDB(B1, 0, 1); PG8_STAGE(PG8_SB(0, 0), b2, voffB);
;             PG8_BAR; PG8_WAIT_L(0); PG8_MMA(0, 1, At, B1); PG8_BAR;
;             PG8_LDA(At, 0, 1); PG8_STAGE(PG8_SA(0, 0), a2, voffA);
;             PG8_BAR; PG8_WAIT_L(0); PG8_MMA(1, 0, At, B0); PG8_BAR; PG8_SCHED;
.LBB0_852:
	s_add_i32 s10, s10, 2
	s_add_u32 s0, s62, s68
	s_addc_u32 s1, s63, s69
	s_add_u32 s38, s0, 0x10000
	s_addc_u32 s39, s1, 0
	s_and_b64 s[0:1], s[70:71], exec
	s_cselect_b32 s73, s47, s39
	s_cselect_b32 s72, s46, s38
	s_add_u32 s74, s7, s68
	s_addc_u32 s75, s8, s69
	s_add_u32 s38, s72, 0x8000
	s_addc_u32 s39, s73, 0
	s_add_i32 s76, 0, 0x10000
	v_add_u32_e32 v142, s76, v200
	ds_read_b128 v[130:133], v142
	ds_read_b128 v[134:137], v142 offset:1024
	ds_read_b128 v[138:141], v142 offset:2048
	ds_read_b128 v[142:145], v142 offset:3072
	s_and_b64 s[0:1], s[70:71], exec
	s_cselect_b32 s71, s27, s75
	s_cselect_b32 s70, s26, s74
	v_lshl_add_u64 v[196:197], v[190:191], 0, s[68:69]
	s_add_i32 m0, s33, 0xc000
	ds_read_b128 v[146:149], v202
	ds_read_b128 v[150:153], v202 offset:1024
	ds_read_b128 v[154:157], v202 offset:2048
	ds_read_b128 v[158:161], v202 offset:3072
	ds_read_b128 v[162:165], v202 offset:4096
	ds_read_b128 v[166:169], v202 offset:5120
	ds_read_b128 v[170:173], v202 offset:6144
	ds_read_b128 v[174:177], v202 offset:7168
	global_load_lds_dwordx4 v[196:197], off
	v_lshl_add_u64 v[196:197], v[188:189], 0, s[68:69]
	s_add_i32 m0, s33, 0xe000
	s_nop 0
	global_load_lds_dwordx4 v[196:197], off
	s_waitcnt lgkmcnt(8)
	s_barrier
	s_waitcnt lgkmcnt(0)
	s_setprio 1
	s_waitcnt lgkmcnt(0)
	v_mfma_f32_16x16x32_bf16 v[126:129], v[130:133], v[146:149], v[126:129]
	v_mfma_f32_16x16x32_bf16 v[122:125], v[138:141], v[146:149], v[122:125]
	v_mfma_f32_16x16x32_bf16 v[118:121], v[130:133], v[154:157], v[118:121]
	v_mfma_f32_16x16x32_bf16 v[114:117], v[138:141], v[154:157], v[114:117]
	v_mfma_f32_16x16x32_bf16 v[110:113], v[130:133], v[162:165], v[110:113]
	v_mfma_f32_16x16x32_bf16 v[106:109], v[138:141], v[162:165], v[106:109]
	v_mfma_f32_16x16x32_bf16 v[102:105], v[130:133], v[170:173], v[102:105]
	v_mfma_f32_16x16x32_bf16 v[94:97], v[138:141], v[170:173], v[94:97]
	v_mfma_f32_16x16x32_bf16 v[126:129], v[134:137], v[150:153], v[126:129]
	v_mfma_f32_16x16x32_bf16 v[122:125], v[142:145], v[150:153], v[122:125]
	v_mfma_f32_16x16x32_bf16 v[118:121], v[134:137], v[158:161], v[118:121]
	v_mfma_f32_16x16x32_bf16 v[114:117], v[142:145], v[158:161], v[114:117]
	v_mfma_f32_16x16x32_bf16 v[110:113], v[134:137], v[166:169], v[110:113]
	v_mfma_f32_16x16x32_bf16 v[106:109], v[142:145], v[166:169], v[106:109]
	v_mfma_f32_16x16x32_bf16 v[102:105], v[134:137], v[174:177], v[102:105]
	v_mfma_f32_16x16x32_bf16 v[94:97], v[142:145], v[174:177], v[94:97]
	s_setprio 0
	s_barrier
	s_add_i32 s74, 0, 0x14000
	s_add_i32 s0, s76, s28
	v_add_u32_e32 v212, s74, v200
	v_lshl_add_u64 v[216:217], s[70:71], 0, v[0:1]
	s_mov_b32 m0, s0
	ds_read_b128 v[196:199], v212
	ds_read_b128 v[204:207], v212 offset:1024
	ds_read_b128 v[208:211], v212 offset:2048
	ds_read_b128 v[212:215], v212 offset:3072
	global_load_lds_dwordx4 v[216:217], off
	v_lshl_add_u64 v[216:217], s[70:71], 0, v[182:183]
	s_add_i32 m0, s0, 0x2000
	s_nop 0
	global_load_lds_dwordx4 v[216:217], off
	s_barrier
	s_waitcnt lgkmcnt(0)
	s_setprio 1
	s_waitcnt lgkmcnt(0)
	v_mfma_f32_16x16x32_bf16 v[90:93], v[196:199], v[146:149], v[90:93]
	v_mfma_f32_16x16x32_bf16 v[82:85], v[208:211], v[146:149], v[82:85]
	v_mfma_f32_16x16x32_bf16 v[74:77], v[196:199], v[154:157], v[74:77]
	v_mfma_f32_16x16x32_bf16 v[66:69], v[208:211], v[154:157], v[66:69]
	v_mfma_f32_16x16x32_bf16 v[58:61], v[196:199], v[162:165], v[58:61]
	v_mfma_f32_16x16x32_bf16 v[50:53], v[208:211], v[162:165], v[50:53]
	v_mfma_f32_16x16x32_bf16 v[42:45], v[196:199], v[170:173], v[42:45]
	v_mfma_f32_16x16x32_bf16 v[38:41], v[208:211], v[170:173], v[38:41]
	v_mfma_f32_16x16x32_bf16 v[90:93], v[204:207], v[150:153], v[90:93]
	v_mfma_f32_16x16x32_bf16 v[82:85], v[212:215], v[150:153], v[82:85]
	v_mfma_f32_16x16x32_bf16 v[74:77], v[204:207], v[158:161], v[74:77]
	v_mfma_f32_16x16x32_bf16 v[66:69], v[212:215], v[158:161], v[66:69]
	v_mfma_f32_16x16x32_bf16 v[58:61], v[204:207], v[166:169], v[58:61]
	v_mfma_f32_16x16x32_bf16 v[50:53], v[212:215], v[166:169], v[50:53]
	v_mfma_f32_16x16x32_bf16 v[42:45], v[204:207], v[174:177], v[42:45]
	v_mfma_f32_16x16x32_bf16 v[38:41], v[212:215], v[174:177], v[38:41]
	s_setprio 0
	s_mov_b32 m0, s33
	v_lshl_add_u64 v[216:217], s[72:73], 0, v[178:179]
	s_barrier
	ds_read_b128 v[146:149], v202 offset:16384
	ds_read_b128 v[150:153], v202 offset:17408
	ds_read_b128 v[154:157], v202 offset:18432
	ds_read_b128 v[158:161], v202 offset:19456
	ds_read_b128 v[162:165], v202 offset:20480
	ds_read_b128 v[166:169], v202 offset:21504
	ds_read_b128 v[170:173], v202 offset:22528
	ds_read_b128 v[174:177], v202 offset:23552
	global_load_lds_dwordx4 v[216:217], off
	v_lshl_add_u64 v[216:217], s[72:73], 0, v[180:181]
	s_mov_b32 m0, s48
	s_nop 0
	global_load_lds_dwordx4 v[216:217], off
	s_barrier
	s_waitcnt lgkmcnt(0)
	s_setprio 1
	s_waitcnt lgkmcnt(0)
	v_mfma_f32_16x16x32_bf16 v[34:37], v[130:133], v[146:149], v[34:37]
	v_mfma_f32_16x16x32_bf16 v[26:29], v[138:141], v[146:149], v[26:29]
	v_mfma_f32_16x16x32_bf16 v[22:25], v[130:133], v[154:157], v[22:25]
	v_mfma_f32_16x16x32_bf16 v[18:21], v[138:141], v[154:157], v[18:21]
	v_mfma_f32_16x16x32_bf16 v[14:17], v[130:133], v[162:165], v[14:17]
	v_mfma_f32_16x16x32_bf16 v[10:13], v[138:141], v[162:165], v[10:13]
	v_mfma_f32_16x16x32_bf16 v[6:9], v[130:133], v[170:173], v[6:9]
	v_mfma_f32_16x16x32_bf16 v[2:5], v[138:141], v[170:173], v[2:5]
	v_mfma_f32_16x16x32_bf16 v[34:37], v[134:137], v[150:153], v[34:37]
	v_mfma_f32_16x16x32_bf16 v[26:29], v[142:145], v[150:153], v[26:29]
	v_mfma_f32_16x16x32_bf16 v[22:25], v[134:137], v[158:161], v[22:25]
	v_mfma_f32_16x16x32_bf16 v[18:21], v[142:145], v[158:161], v[18:21]
	v_mfma_f32_16x16x32_bf16 v[14:17], v[134:137], v[166:169], v[14:17]
	v_mfma_f32_16x16x32_bf16 v[10:13], v[142:145], v[166:169], v[10:13]
	v_mfma_f32_16x16x32_bf16 v[6:9], v[134:137], v[174:177], v[6:9]
	v_mfma_f32_16x16x32_bf16 v[2:5], v[142:145], v[174:177], v[2:5]
	s_setprio 0
	s_barrier
; #define PG8_STAGE(bufoff, gbase, voff) do { _Pragma("unroll") for (int _i = 0; _i < 2; ++_i) \
;         __builtin_amdgcn_global_load_lds((const unsigned*)((const char*)(gbase) + (voff)[_i]), (LAS unsigned*)(lds + (bufoff) + ldsw + _i * 8192), 16, 0, 0); } while (0)
; #define PG8_LDA(dst, b, h) do { _Pragma("unroll") for (int m = 0; m < 4; ++m) _Pragma("unroll") for (int k = 0; k < 2; ++k) dst[m][k] = *(const LAS bf16x8*)(lds + PG8_SA(b, h) + aoff + m * 2048 + k * 1024); } while (0)
; #define PG8_LDB(dst, b, h) do { _Pragma("unroll") for (int n = 0; n < 2; ++n) _Pragma("unroll") for (int k = 0; k < 2; ++k) dst[n][k] = *(const LAS bf16x8*)(lds + PG8_SB(b, h) + boff + n * 2048 + k * 1024); } while (0)
; #define PG8_MMA(ai, bj, At, Bt) do { __builtin_amdgcn_s_setprio(1); _Pragma("unroll") for (int m = 0; m < 4; ++m) _Pragma("unroll") for (int n = 0; n < 2; ++n) _Pragma("unroll") for (int k = 0; k < 2; ++k) \
;         acc[ai][bj][m][n] = __builtin_amdgcn_mfma_f32_16x16x32_bf16(Bt[n][k], At[m][k], acc[ai][bj][m][n], 0, 0, 0); __builtin_amdgcn_s_setprio(0); } while (0)
; #define PG8_WAIT_V(n) asm volatile("s_waitcnt vmcnt(" #n ")" ::: "memory")
; #define PG8_WAIT_L(n) asm volatile("s_waitcnt lgkmcnt(" #n ")" ::: "memory")
; #define PG8_BAR __builtin_amdgcn_s_barrier()
; #define PG8_SCHED __builtin_amdgcn_sched_barrier(0)
; template <class Epi, bool DYN = false>
; __device__ __forceinline__ void gemm_phase(LAS unsigned char* lds, const Gemm g, const Epi& E, int wave, unsigned* ctr = nullptr) {
;     ...
;             PG8_STAGE(PG8_SB(0, 1), b2 + hstepB, voffB);
;             PG8_WAIT_V(6); PG8_BAR; PG8_MMA(1, 1, At, B1); PG8_BAR;
;             PG8_LDB(B0, 1, 0); PG8_SCHED; PG8_LDA(At, 1, 0); PG8_STAGE(PG8_SA(0, 1), a2 + hstepA, voffA);
;             PG8_WAIT_L(8); PG8_BAR; PG8_WAIT_L(0); PG8_MMA(0, 0, At, B0); PG8_BAR; PG8_SCHED;
;             PG8_LDB(B1, 1, 1); PG8_STAGE(PG8_SB(1, 0), b3, voffB);
	s_add_u32 s0, s70, 0x4000
	s_addc_u32 s1, s71, 0
	s_add_i32 s74, s74, s28
	v_lshl_add_u64 v[130:131], s[0:1], 0, v[0:1]
	s_mov_b32 m0, s74
	s_nop 0
	global_load_lds_dwordx4 v[130:131], off
	v_lshl_add_u64 v[130:131], s[0:1], 0, v[182:183]
	s_add_i32 m0, s74, 0x2000
	s_nop 0
	global_load_lds_dwordx4 v[130:131], off
	s_waitcnt vmcnt(6)
	s_barrier
	s_setprio 1
	v_mfma_f32_16x16x32_bf16 v[98:101], v[196:199], v[146:149], v[98:101]
	v_mfma_f32_16x16x32_bf16 v[86:89], v[208:211], v[146:149], v[86:89]
	v_mfma_f32_16x16x32_bf16 v[78:81], v[196:199], v[154:157], v[78:81]
	v_mfma_f32_16x16x32_bf16 v[70:73], v[208:211], v[154:157], v[70:73]
	v_mfma_f32_16x16x32_bf16 v[62:65], v[196:199], v[162:165], v[62:65]
	v_mfma_f32_16x16x32_bf16 v[54:57], v[208:211], v[162:165], v[54:57]
	v_mfma_f32_16x16x32_bf16 v[46:49], v[196:199], v[170:173], v[46:49]
	v_mfma_f32_16x16x32_bf16 v[30:33], v[208:211], v[170:173], v[30:33]
	v_mfma_f32_16x16x32_bf16 v[98:101], v[204:207], v[150:153], v[98:101]
	v_mfma_f32_16x16x32_bf16 v[86:89], v[212:215], v[150:153], v[86:89]
	v_mfma_f32_16x16x32_bf16 v[78:81], v[204:207], v[158:161], v[78:81]
	v_mfma_f32_16x16x32_bf16 v[70:73], v[212:215], v[158:161], v[70:73]
	v_mfma_f32_16x16x32_bf16 v[62:65], v[204:207], v[166:169], v[62:65]
	v_mfma_f32_16x16x32_bf16 v[54:57], v[212:215], v[166:169], v[54:57]
	v_mfma_f32_16x16x32_bf16 v[46:49], v[204:207], v[174:177], v[46:49]
	v_mfma_f32_16x16x32_bf16 v[30:33], v[212:215], v[174:177], v[30:33]
	s_setprio 0
	s_add_i32 s74, 0, 0x18000
	v_add_u32_e32 v130, s74, v200
	s_barrier
	ds_read_b128 v[196:199], v130
	ds_read_b128 v[204:207], v130 offset:1024
	ds_read_b128 v[208:211], v130 offset:2048
	ds_read_b128 v[212:215], v130 offset:3072
	s_add_u32 s0, s72, 0x4000
	s_addc_u32 s1, s73, 0
	s_mov_b32 m0, s86
	v_lshl_add_u64 v[130:131], s[0:1], 0, v[178:179]
	ds_read_b128 v[146:149], v202 offset:32768
	ds_read_b128 v[150:153], v202 offset:33792
	ds_read_b128 v[154:157], v202 offset:34816
	ds_read_b128 v[158:161], v202 offset:35840
	ds_read_b128 v[162:165], v202 offset:36864
	ds_read_b128 v[166:169], v202 offset:37888
	ds_read_b128 v[170:173], v202 offset:38912
	ds_read_b128 v[174:177], v202 offset:39936
	global_load_lds_dwordx4 v[130:131], off
	v_lshl_add_u64 v[130:131], s[0:1], 0, v[180:181]
	s_mov_b32 m0, s87
	s_nop 0
	global_load_lds_dwordx4 v[130:131], off
	s_waitcnt lgkmcnt(8)
	s_barrier
	s_waitcnt lgkmcnt(0)
	s_setprio 1
	s_waitcnt lgkmcnt(0)
	v_mfma_f32_16x16x32_bf16 v[126:129], v[196:199], v[146:149], v[126:129]
	v_mfma_f32_16x16x32_bf16 v[122:125], v[208:211], v[146:149], v[122:125]
	v_mfma_f32_16x16x32_bf16 v[118:121], v[196:199], v[154:157], v[118:121]
	v_mfma_f32_16x16x32_bf16 v[114:117], v[208:211], v[154:157], v[114:117]
	v_mfma_f32_16x16x32_bf16 v[110:113], v[196:199], v[162:165], v[110:113]
	v_mfma_f32_16x16x32_bf16 v[106:109], v[208:211], v[162:165], v[106:109]
	v_mfma_f32_16x16x32_bf16 v[102:105], v[196:199], v[170:173], v[102:105]
	v_mfma_f32_16x16x32_bf16 v[94:97], v[208:211], v[170:173], v[94:97]
	v_mfma_f32_16x16x32_bf16 v[126:129], v[204:207], v[150:153], v[126:129]
	v_mfma_f32_16x16x32_bf16 v[122:125], v[212:215], v[150:153], v[122:125]
	v_mfma_f32_16x16x32_bf16 v[118:121], v[204:207], v[158:161], v[118:121]
	v_mfma_f32_16x16x32_bf16 v[114:117], v[212:215], v[158:161], v[114:117]
	v_mfma_f32_16x16x32_bf16 v[110:113], v[204:207], v[166:169], v[110:113]
	v_mfma_f32_16x16x32_bf16 v[106:109], v[212:215], v[166:169], v[106:109]
	v_mfma_f32_16x16x32_bf16 v[102:105], v[204:207], v[174:177], v[102:105]
	v_mfma_f32_16x16x32_bf16 v[94:97], v[212:215], v[174:177], v[94:97]
	s_setprio 0
	s_barrier
	s_add_u32 s0, s70, 0x8000
	v_add_u32_e32 v130, 0, v200
	s_addc_u32 s1, s71, 0
	s_add_i32 s72, s74, s28
	v_add_u32_e32 v142, 0x1c000, v130
	v_lshl_add_u64 v[216:217], s[0:1], 0, v[0:1]
	s_mov_b32 m0, s72
	ds_read_b128 v[130:133], v142
	ds_read_b128 v[134:137], v142 offset:1024
	ds_read_b128 v[138:141], v142 offset:2048
	ds_read_b128 v[142:145], v142 offset:3072
	global_load_lds_dwordx4 v[216:217], off
	v_lshl_add_u64 v[216:217], s[0:1], 0, v[182:183]
	s_add_i32 m0, s72, 0x2000
	s_nop 0
	global_load_lds_dwordx4 v[216:217], off
	s_barrier
; #define PG8_STAGE(bufoff, gbase, voff) do { _Pragma("unroll") for (int _i = 0; _i < 2; ++_i) \
;         __builtin_amdgcn_global_load_lds((const unsigned*)((const char*)(gbase) + (voff)[_i]), (LAS unsigned*)(lds + (bufoff) + ldsw + _i * 8192), 16, 0, 0); } while (0)
; #define PG8_LDA(dst, b, h) do { _Pragma("unroll") for (int m = 0; m < 4; ++m) _Pragma("unroll") for (int k = 0; k < 2; ++k) dst[m][k] = *(const LAS bf16x8*)(lds + PG8_SA(b, h) + aoff + m * 2048 + k * 1024); } while (0)
; #define PG8_MMA(ai, bj, At, Bt) do { __builtin_amdgcn_s_setprio(1); _Pragma("unroll") for (int m = 0; m < 4; ++m) _Pragma("unroll") for (int n = 0; n < 2; ++n) _Pragma("unroll") for (int k = 0; k < 2; ++k) \
;         acc[ai][bj][m][n] = __builtin_amdgcn_mfma_f32_16x16x32_bf16(Bt[n][k], At[m][k], acc[ai][bj][m][n], 0, 0, 0); __builtin_amdgcn_s_setprio(0); } while (0)
; #define PG8_WAIT_L(n) asm volatile("s_waitcnt lgkmcnt(" #n ")" ::: "memory")
; #define PG8_BAR __builtin_amdgcn_s_barrier()
; #define PG8_SCHED __builtin_amdgcn_sched_barrier(0)
; template <class Epi, bool DYN = false>
; __device__ __forceinline__ void gemm_phase(LAS unsigned char* lds, const Gemm g, const Epi& E, int wave, unsigned* ctr = nullptr) {
;     ...
;     auto publish = [&](int si) { if (tid == 0) { int wg = -1;
;             if (ticket < rng_cnt(xcd)) wg = rng_start(xcd) + ticket;
;             else { for (int k = 1; k < 8; ++k) { const int x2 = (xcd + k) & 7; const int t2 = (int)__hip_atomic_fetch_add(ctr + x2 * 16, 1u, __ATOMIC_RELAXED, __HIP_MEMORY_SCOPE_AGENT); if (t2 < rng_cnt(x2)) { wg = rng_start(x2) + t2; break; } } }
;             slot[si] = wg; } };
;     ...
;             PG8_BAR; PG8_WAIT_L(0); PG8_MMA(0, 1, At, B1); PG8_BAR;
;             PG8_LDA(At, 1, 1); PG8_STAGE(PG8_SA(1, 0), a3, voffA);
;             PG8_BAR; PG8_WAIT_L(0); PG8_MMA(1, 0, At, B0); PG8_BAR; PG8_SCHED;
;             if (DYN && t == 0) publish((ui + 1) & 1);
	s_waitcnt lgkmcnt(0)
	s_setprio 1
	s_waitcnt lgkmcnt(0)
	v_mfma_f32_16x16x32_bf16 v[90:93], v[130:133], v[146:149], v[90:93]
	v_mfma_f32_16x16x32_bf16 v[82:85], v[138:141], v[146:149], v[82:85]
	v_mfma_f32_16x16x32_bf16 v[74:77], v[130:133], v[154:157], v[74:77]
	v_mfma_f32_16x16x32_bf16 v[66:69], v[138:141], v[154:157], v[66:69]
	v_mfma_f32_16x16x32_bf16 v[58:61], v[130:133], v[162:165], v[58:61]
	v_mfma_f32_16x16x32_bf16 v[50:53], v[138:141], v[162:165], v[50:53]
	v_mfma_f32_16x16x32_bf16 v[42:45], v[130:133], v[170:173], v[42:45]
	v_mfma_f32_16x16x32_bf16 v[38:41], v[138:141], v[170:173], v[38:41]
	v_mfma_f32_16x16x32_bf16 v[90:93], v[134:137], v[150:153], v[90:93]
	v_mfma_f32_16x16x32_bf16 v[82:85], v[142:145], v[150:153], v[82:85]
	v_mfma_f32_16x16x32_bf16 v[74:77], v[134:137], v[158:161], v[74:77]
	v_mfma_f32_16x16x32_bf16 v[66:69], v[142:145], v[158:161], v[66:69]
	v_mfma_f32_16x16x32_bf16 v[58:61], v[134:137], v[166:169], v[58:61]
	v_mfma_f32_16x16x32_bf16 v[50:53], v[142:145], v[166:169], v[50:53]
	v_mfma_f32_16x16x32_bf16 v[42:45], v[134:137], v[174:177], v[42:45]
	v_mfma_f32_16x16x32_bf16 v[38:41], v[142:145], v[174:177], v[38:41]
	s_setprio 0
	s_mov_b32 m0, s88
	v_lshl_add_u64 v[216:217], s[38:39], 0, v[178:179]
	s_barrier
	ds_read_b128 v[170:173], v202 offset:49152
	ds_read_b128 v[174:177], v202 offset:50176
	ds_read_b128 v[162:165], v202 offset:51200
	ds_read_b128 v[166:169], v202 offset:52224
	ds_read_b128 v[154:157], v202 offset:53248
	ds_read_b128 v[158:161], v202 offset:54272
	ds_read_b128 v[146:149], v202 offset:55296
	ds_read_b128 v[150:153], v202 offset:56320
	global_load_lds_dwordx4 v[216:217], off
	v_lshl_add_u64 v[216:217], s[38:39], 0, v[180:181]
	s_mov_b32 m0, s89
	s_nop 0
	global_load_lds_dwordx4 v[216:217], off
	s_barrier
	s_waitcnt lgkmcnt(0)
	s_setprio 1
	s_waitcnt lgkmcnt(0)
	v_mfma_f32_16x16x32_bf16 v[34:37], v[196:199], v[170:173], v[34:37]
	v_mfma_f32_16x16x32_bf16 v[26:29], v[208:211], v[170:173], v[26:29]
	v_mfma_f32_16x16x32_bf16 v[22:25], v[196:199], v[162:165], v[22:25]
	v_mfma_f32_16x16x32_bf16 v[18:21], v[208:211], v[162:165], v[18:21]
	v_mfma_f32_16x16x32_bf16 v[14:17], v[196:199], v[154:157], v[14:17]
	v_mfma_f32_16x16x32_bf16 v[10:13], v[208:211], v[154:157], v[10:13]
	v_mfma_f32_16x16x32_bf16 v[6:9], v[196:199], v[146:149], v[6:9]
	v_mfma_f32_16x16x32_bf16 v[2:5], v[208:211], v[146:149], v[2:5]
	v_mfma_f32_16x16x32_bf16 v[34:37], v[204:207], v[174:177], v[34:37]
	v_mfma_f32_16x16x32_bf16 v[26:29], v[212:215], v[174:177], v[26:29]
	v_mfma_f32_16x16x32_bf16 v[22:25], v[204:207], v[166:169], v[22:25]
	v_mfma_f32_16x16x32_bf16 v[18:21], v[212:215], v[166:169], v[18:21]
	v_mfma_f32_16x16x32_bf16 v[14:17], v[204:207], v[158:161], v[14:17]
	v_mfma_f32_16x16x32_bf16 v[10:13], v[212:215], v[158:161], v[10:13]
	v_mfma_f32_16x16x32_bf16 v[6:9], v[204:207], v[150:153], v[6:9]
	v_mfma_f32_16x16x32_bf16 v[2:5], v[212:215], v[150:153], v[2:5]
	s_setprio 0
	s_barrier
	v_or_b32_e32 v196, s10, v192
	v_cmp_eq_u32_e64 s[38:39], 0, v196
	s_and_saveexec_b64 s[72:73], s[38:39]
	s_cbranch_execz .LBB0_847
	v_cmp_lt_i32_e32 vcc, s91, v193
	v_add_u32_e32 v203, s61, v193
	v_mov_b32_e32 v204, v203
	s_and_saveexec_b64 s[74:75], vcc
	s_cbranch_execz .LBB0_846
	v_readlane_b32 s0, v254, 11
	s_nop 1
	v_mov_b32_e32 v196, s0
	ds_read_b32 v196, v196
	v_mov_b32_e32 v204, -1
	s_waitcnt lgkmcnt(0)
	v_readfirstlane_b32 s0, v196
	s_cmp_eq_u32 s0, 8
	s_cbranch_scc1 .LBB0_846
	v_mov_b64_e32 v[196:197], s[40:41]
	s_waitcnt vmcnt(0)
	flat_atomic_add v196, v[196:197], v224 sc0
	s_waitcnt vmcnt(0) lgkmcnt(0)
	v_cmp_lt_i32_e64 s[38:39], s91, v196
	v_add_u32_e32 v204, s3, v196
	s_and_saveexec_b64 s[0:1], s[38:39]
	s_cbranch_execz .LBB0_845
	v_mov_b64_e32 v[196:197], s[42:43]
	flat_atomic_add v196, v[196:197], v224 sc0
	s_waitcnt vmcnt(0) lgkmcnt(0)
	v_cmp_lt_i32_e64 s[38:39], s91, v196
	v_add_u32_e32 v204, s2, v196
	s_and_saveexec_b64 s[76:77], s[38:39]
	s_cbranch_execz .LBB0_844
	v_mov_b64_e32 v[196:197], s[44:45]
	flat_atomic_add v196, v[196:197], v224 sc0
	s_waitcnt vmcnt(0) lgkmcnt(0)
	v_cmp_lt_i32_e64 s[38:39], s91, v196
	v_add_u32_e32 v204, s22, v196
	s_and_saveexec_b64 s[78:79], s[38:39]
	s_cbranch_execz .LBB0_843
	v_mov_b64_e32 v[196:197], s[50:51]
	flat_atomic_add v196, v[196:197], v224 sc0
	s_waitcnt vmcnt(0) lgkmcnt(0)
	v_cmp_lt_i32_e64 s[38:39], s91, v196
	v_add_u32_e32 v204, s23, v196
	s_and_saveexec_b64 s[80:81], s[38:39]
	s_cbranch_execz .LBB0_842
	v_mov_b64_e32 v[196:197], s[54:55]
	flat_atomic_add v196, v[196:197], v224 sc0
	s_movk_i32 s92, 0x60
	s_waitcnt vmcnt(0) lgkmcnt(0)
	v_cmp_lt_i32_e64 s[38:39], s91, v196
	v_add_u32_e32 v204, s60, v196
	s_and_saveexec_b64 s[82:83], s[38:39]
	s_cbranch_execz .LBB0_841
	v_mov_b64_e32 v[196:197], s[58:59]
	flat_atomic_add v196, v[196:197], v224 sc0
	v_readlane_b32 s84, v254, 52
	s_waitcnt vmcnt(0) lgkmcnt(0)
	v_cmp_lt_i32_e64 s[38:39], s91, v196
	v_add_u32_e32 v204, s84, v196
	s_and_saveexec_b64 s[84:85], s[38:39]
	s_cbranch_execz .LBB0_840
	v_readlane_b32 s38, v254, 54
	v_readlane_b32 s39, v254, 55
	s_nop 1
	v_mov_b64_e32 v[196:197], s[38:39]
	flat_atomic_add v196, v[196:197], v224 sc0
	v_readlane_b32 s38, v254, 56
	s_waitcnt vmcnt(0) lgkmcnt(0)
	s_nop 0
	v_add_u32_e32 v197, s38, v196
	v_cmp_gt_i32_e64 s[38:39], s92, v196
	s_nop 1
	v_cndmask_b32_e64 v204, -1, v197, s[38:39]
	s_branch .LBB0_840

; #define PG8_STAGE(bufoff, gbase, voff) do { _Pragma("unroll") for (int _i = 0; _i < 2; ++_i) \
;         __builtin_amdgcn_global_load_lds((const unsigned*)((const char*)(gbase) + (voff)[_i]), (LAS unsigned*)(lds + (bufoff) + ldsw + _i * 8192), 16, 0, 0); } while (0)
; #define PG8_LDA(dst, b, h) do { _Pragma("unroll") for (int m = 0; m < 4; ++m) _Pragma("unroll") for (int k = 0; k < 2; ++k) dst[m][k] = *(const LAS bf16x8*)(lds + PG8_SA(b, h) + aoff + m * 2048 + k * 1024); } while (0)
; #define PG8_LDB(dst, b, h) do { _Pragma("unroll") for (int n = 0; n < 2; ++n) _Pragma("unroll") for (int k = 0; k < 2; ++k) dst[n][k] = *(const LAS bf16x8*)(lds + PG8_SB(b, h) + boff + n * 2048 + k * 1024); } while (0)
; #define PG8_MMA(ai, bj, At, Bt) do { __builtin_amdgcn_s_setprio(1); _Pragma("unroll") for (int m = 0; m < 4; ++m) _Pragma("unroll") for (int n = 0; n < 2; ++n) _Pragma("unroll") for (int k = 0; k < 2; ++k) \
;         acc[ai][bj][m][n] = __builtin_amdgcn_mfma_f32_16x16x32_bf16(Bt[n][k], At[m][k], acc[ai][bj][m][n], 0, 0, 0); __builtin_amdgcn_s_setprio(0); } while (0)
; template <class Epi, bool DYN = false>
; __device__ __forceinline__ void gemm_phase(LAS unsigned char* lds, const Gemm g, const Epi& E, int wave, unsigned* ctr = nullptr) {
;     ...
;         for (int t = 0; t < nt; t += 2) {
;             const bool last = (t == nt - 2);
;             if (DYN && last) { const int nw = __builtin_amdgcn_readfirstlane(slot[(ui + 1) & 1]); has_next = nw >= 0;
;                 if (has_next) { decode(nw, nxt); nA = (const char*)g.A + (size_t)nxt.pm * tstepA; nB = (const char*)g.Bt + (size_t)nxt.pn * tstepB; } }
;             const char* a1 = cA + (size_t)(t + 1) * kstepA;
;             const char* a2 = last ? nA : cA + (size_t)(t + 2) * kstepA; const char* b2 = last ? nB : cB + (size_t)(t + 2) * kstepB;
;             const char* a3 = a2 + kstepA; const char* b3 = b2 + kstepB;
;             PG8_LDB(B0, 0, 0); PG8_SCHED; PG8_LDA(At, 0, 0); PG8_STAGE(PG8_SA(1, 1), a1 + hstepA, voffA);
;             PG8_WAIT_L(8); PG8_BAR; PG8_WAIT_L(0); PG8_MMA(0, 0, At, B0); PG8_BAR; PG8_SCHED;
;             PG8_LDB(B1, 0, 1); PG8_STAGE(PG8_SB(0, 0), b2, voffB);
;             PG8_BAR; PG8_WAIT_L(0); PG8_MMA(0, 1, At, B1); PG8_BAR;
;             PG8_LDA(At, 0, 1); PG8_STAGE(PG8_SA(0, 0), a2, voffA);
;             PG8_BAR; PG8_WAIT_L(0); PG8_MMA(1, 0, At, B0); PG8_BAR; PG8_SCHED;
.LBB0_924:
	s_add_i32 s7, s7, 2
	s_add_u32 s0, s68, s46
	s_addc_u32 s1, s69, s47
	s_add_u32 s8, s0, 0x10000
	s_addc_u32 s9, s1, 0
	s_and_b64 s[0:1], s[74:75], exec
	s_cselect_b32 s77, s71, s9
	s_cselect_b32 s76, s70, s8
	s_add_u32 s8, s4, s46
	s_addc_u32 s9, s5, s47
	s_add_u32 s38, s76, 0x8000
	s_addc_u32 s39, s77, 0
	s_add_i32 s10, 0, 0x10000
	v_add_u32_e32 v0, s10, v214
	ds_read_b128 v[130:133], v0
	ds_read_b128 v[134:137], v0 offset:1024
	ds_read_b128 v[138:141], v0 offset:2048
	ds_read_b128 v[142:145], v0 offset:3072
	s_and_b64 s[0:1], s[74:75], exec
	s_cselect_b32 s75, s65, s9
	s_cselect_b32 s74, s64, s8
	v_lshl_add_u64 v[196:197], v[200:201], 0, s[46:47]
	s_add_i32 m0, s19, 0xc000
	ds_read_b128 v[146:149], v215
	ds_read_b128 v[150:153], v215 offset:1024
	ds_read_b128 v[154:157], v215 offset:2048
	ds_read_b128 v[158:161], v215 offset:3072
	ds_read_b128 v[162:165], v215 offset:4096
	ds_read_b128 v[166:169], v215 offset:5120
	ds_read_b128 v[170:173], v215 offset:6144
	ds_read_b128 v[174:177], v215 offset:7168
	global_load_lds_dwordx4 v[196:197], off
	v_lshl_add_u64 v[196:197], v[192:193], 0, s[46:47]
	s_add_i32 m0, s19, 0xe000
	s_nop 0
	global_load_lds_dwordx4 v[196:197], off
	s_waitcnt lgkmcnt(8)
	s_barrier
	s_waitcnt lgkmcnt(0)
	s_setprio 1
	s_waitcnt lgkmcnt(0)
	v_mfma_f32_16x16x32_bf16 v[2:5], v[130:133], v[146:149], v[2:5]
	v_mfma_f32_16x16x32_bf16 v[30:33], v[138:141], v[146:149], v[30:33]
	v_mfma_f32_16x16x32_bf16 v[26:29], v[130:133], v[154:157], v[26:29]
	v_mfma_f32_16x16x32_bf16 v[22:25], v[138:141], v[154:157], v[22:25]
	v_mfma_f32_16x16x32_bf16 v[18:21], v[130:133], v[162:165], v[18:21]
	v_mfma_f32_16x16x32_bf16 v[14:17], v[138:141], v[162:165], v[14:17]
	v_mfma_f32_16x16x32_bf16 v[10:13], v[130:133], v[170:173], v[10:13]
	v_mfma_f32_16x16x32_bf16 v[6:9], v[138:141], v[170:173], v[6:9]
	v_mfma_f32_16x16x32_bf16 v[2:5], v[134:137], v[150:153], v[2:5]
	v_mfma_f32_16x16x32_bf16 v[30:33], v[142:145], v[150:153], v[30:33]
	v_mfma_f32_16x16x32_bf16 v[26:29], v[134:137], v[158:161], v[26:29]
	v_mfma_f32_16x16x32_bf16 v[22:25], v[142:145], v[158:161], v[22:25]
	v_mfma_f32_16x16x32_bf16 v[18:21], v[134:137], v[166:169], v[18:21]
	v_mfma_f32_16x16x32_bf16 v[14:17], v[142:145], v[166:169], v[14:17]
	v_mfma_f32_16x16x32_bf16 v[10:13], v[134:137], v[174:177], v[10:13]
	v_mfma_f32_16x16x32_bf16 v[6:9], v[142:145], v[174:177], v[6:9]
	s_setprio 0
	s_barrier
	s_add_i32 s8, 0, 0x14000
	s_add_i32 s0, s10, s17
	v_add_u32_e32 v0, s8, v214
	v_lshl_add_u64 v[220:221], s[74:75], 0, v[180:181]
	s_mov_b32 m0, s0
	ds_read_b128 v[216:219], v0
	ds_read_b128 v[244:247], v0 offset:1024
	ds_read_b128 v[232:235], v0 offset:2048
	ds_read_b128 v[196:199], v0 offset:3072
	global_load_lds_dwordx4 v[220:221], off
	v_lshl_add_u64 v[220:221], s[74:75], 0, v[184:185]
	s_add_i32 m0, s0, 0x2000
	s_nop 0
	global_load_lds_dwordx4 v[220:221], off
	s_barrier
	s_waitcnt lgkmcnt(0)
	s_setprio 1
	s_waitcnt lgkmcnt(0)
	v_mfma_f32_16x16x32_bf16 v[94:97], v[216:219], v[146:149], v[94:97]
	v_mfma_f32_16x16x32_bf16 v[90:93], v[232:235], v[146:149], v[90:93]
	v_mfma_f32_16x16x32_bf16 v[86:89], v[216:219], v[154:157], v[86:89]
	v_mfma_f32_16x16x32_bf16 v[82:85], v[232:235], v[154:157], v[82:85]
	v_mfma_f32_16x16x32_bf16 v[78:81], v[216:219], v[162:165], v[78:81]
	v_mfma_f32_16x16x32_bf16 v[74:77], v[232:235], v[162:165], v[74:77]
	v_mfma_f32_16x16x32_bf16 v[70:73], v[216:219], v[170:173], v[70:73]
	v_mfma_f32_16x16x32_bf16 v[66:69], v[232:235], v[170:173], v[66:69]
	v_mfma_f32_16x16x32_bf16 v[94:97], v[244:247], v[150:153], v[94:97]
	v_mfma_f32_16x16x32_bf16 v[90:93], v[196:199], v[150:153], v[90:93]
	v_mfma_f32_16x16x32_bf16 v[86:89], v[244:247], v[158:161], v[86:89]
	v_mfma_f32_16x16x32_bf16 v[82:85], v[196:199], v[158:161], v[82:85]
	v_mfma_f32_16x16x32_bf16 v[78:81], v[244:247], v[166:169], v[78:81]
	v_mfma_f32_16x16x32_bf16 v[74:77], v[196:199], v[166:169], v[74:77]
	v_mfma_f32_16x16x32_bf16 v[70:73], v[244:247], v[174:177], v[70:73]
	v_mfma_f32_16x16x32_bf16 v[66:69], v[196:199], v[174:177], v[66:69]
	s_setprio 0
	s_mov_b32 m0, s19
	v_lshl_add_u64 v[220:221], s[76:77], 0, v[178:179]
	s_barrier
	ds_read_b128 v[146:149], v215 offset:16384
	ds_read_b128 v[150:153], v215 offset:17408
	ds_read_b128 v[154:157], v215 offset:18432
	ds_read_b128 v[158:161], v215 offset:19456
	ds_read_b128 v[162:165], v215 offset:20480
	ds_read_b128 v[166:169], v215 offset:21504
	ds_read_b128 v[170:173], v215 offset:22528
	ds_read_b128 v[174:177], v215 offset:23552
	global_load_lds_dwordx4 v[220:221], off
	v_lshl_add_u64 v[220:221], s[76:77], 0, v[182:183]
	s_mov_b32 m0, s23
	s_nop 0
	global_load_lds_dwordx4 v[220:221], off
	s_barrier
	s_waitcnt lgkmcnt(0)
	s_setprio 1
	s_waitcnt lgkmcnt(0)
	v_mfma_f32_16x16x32_bf16 v[62:65], v[130:133], v[146:149], v[62:65]
	v_mfma_f32_16x16x32_bf16 v[58:61], v[138:141], v[146:149], v[58:61]
	v_mfma_f32_16x16x32_bf16 v[54:57], v[130:133], v[154:157], v[54:57]
	v_mfma_f32_16x16x32_bf16 v[50:53], v[138:141], v[154:157], v[50:53]
	v_mfma_f32_16x16x32_bf16 v[46:49], v[130:133], v[162:165], v[46:49]
	v_mfma_f32_16x16x32_bf16 v[42:45], v[138:141], v[162:165], v[42:45]
	v_mfma_f32_16x16x32_bf16 v[38:41], v[130:133], v[170:173], v[38:41]
	v_mfma_f32_16x16x32_bf16 v[34:37], v[138:141], v[170:173], v[34:37]
	v_mfma_f32_16x16x32_bf16 v[62:65], v[134:137], v[150:153], v[62:65]
	v_mfma_f32_16x16x32_bf16 v[58:61], v[142:145], v[150:153], v[58:61]
	v_mfma_f32_16x16x32_bf16 v[54:57], v[134:137], v[158:161], v[54:57]
	v_mfma_f32_16x16x32_bf16 v[50:53], v[142:145], v[158:161], v[50:53]
	v_mfma_f32_16x16x32_bf16 v[46:49], v[134:137], v[166:169], v[46:49]
	v_mfma_f32_16x16x32_bf16 v[42:45], v[142:145], v[166:169], v[42:45]
	v_mfma_f32_16x16x32_bf16 v[38:41], v[134:137], v[174:177], v[38:41]
	v_mfma_f32_16x16x32_bf16 v[34:37], v[142:145], v[174:177], v[34:37]
	s_setprio 0
	s_barrier
; #define PG8_STAGE(bufoff, gbase, voff) do { _Pragma("unroll") for (int _i = 0; _i < 2; ++_i) \
;         __builtin_amdgcn_global_load_lds((const unsigned*)((const char*)(gbase) + (voff)[_i]), (LAS unsigned*)(lds + (bufoff) + ldsw + _i * 8192), 16, 0, 0); } while (0)
; #define PG8_LDA(dst, b, h) do { _Pragma("unroll") for (int m = 0; m < 4; ++m) _Pragma("unroll") for (int k = 0; k < 2; ++k) dst[m][k] = *(const LAS bf16x8*)(lds + PG8_SA(b, h) + aoff + m * 2048 + k * 1024); } while (0)
; #define PG8_LDB(dst, b, h) do { _Pragma("unroll") for (int n = 0; n < 2; ++n) _Pragma("unroll") for (int k = 0; k < 2; ++k) dst[n][k] = *(const LAS bf16x8*)(lds + PG8_SB(b, h) + boff + n * 2048 + k * 1024); } while (0)
; #define PG8_MMA(ai, bj, At, Bt) do { __builtin_amdgcn_s_setprio(1); _Pragma("unroll") for (int m = 0; m < 4; ++m) _Pragma("unroll") for (int n = 0; n < 2; ++n) _Pragma("unroll") for (int k = 0; k < 2; ++k) \
;         acc[ai][bj][m][n] = __builtin_amdgcn_mfma_f32_16x16x32_bf16(Bt[n][k], At[m][k], acc[ai][bj][m][n], 0, 0, 0); __builtin_amdgcn_s_setprio(0); } while (0)
; #define PG8_WAIT_V(n) asm volatile("s_waitcnt vmcnt(" #n ")" ::: "memory")
; #define PG8_WAIT_L(n) asm volatile("s_waitcnt lgkmcnt(" #n ")" ::: "memory")
; #define PG8_BAR __builtin_amdgcn_s_barrier()
; #define PG8_SCHED __builtin_amdgcn_sched_barrier(0)
; template <class Epi, bool DYN = false>
; __device__ __forceinline__ void gemm_phase(LAS unsigned char* lds, const Gemm g, const Epi& E, int wave, unsigned* ctr = nullptr) {
;     ...
;             PG8_STAGE(PG8_SB(0, 1), b2 + hstepB, voffB);
;             PG8_WAIT_V(6); PG8_BAR; PG8_MMA(1, 1, At, B1); PG8_BAR;
;             PG8_LDB(B0, 1, 0); PG8_SCHED; PG8_LDA(At, 1, 0); PG8_STAGE(PG8_SA(0, 1), a2 + hstepA, voffA);
;             PG8_WAIT_L(8); PG8_BAR; PG8_WAIT_L(0); PG8_MMA(0, 0, At, B0); PG8_BAR; PG8_SCHED;
;             PG8_LDB(B1, 1, 1); PG8_STAGE(PG8_SB(1, 0), b3, voffB);
	s_add_u32 s0, s74, 0x4000
	s_addc_u32 s1, s75, 0
	s_add_i32 s8, s8, s17
	v_lshl_add_u64 v[130:131], s[0:1], 0, v[180:181]
	s_mov_b32 m0, s8
	s_nop 0
	global_load_lds_dwordx4 v[130:131], off
	v_lshl_add_u64 v[130:131], s[0:1], 0, v[184:185]
	s_add_i32 m0, s8, 0x2000
	s_nop 0
	global_load_lds_dwordx4 v[130:131], off
	s_waitcnt vmcnt(6)
	s_barrier
	s_setprio 1
	v_mfma_f32_16x16x32_bf16 v[126:129], v[216:219], v[146:149], v[126:129]
	v_mfma_f32_16x16x32_bf16 v[122:125], v[232:235], v[146:149], v[122:125]
	v_mfma_f32_16x16x32_bf16 v[118:121], v[216:219], v[154:157], v[118:121]
	v_mfma_f32_16x16x32_bf16 v[114:117], v[232:235], v[154:157], v[114:117]
	v_mfma_f32_16x16x32_bf16 v[110:113], v[216:219], v[162:165], v[110:113]
	v_mfma_f32_16x16x32_bf16 v[106:109], v[232:235], v[162:165], v[106:109]
	v_mfma_f32_16x16x32_bf16 v[102:105], v[216:219], v[170:173], v[102:105]
	v_mfma_f32_16x16x32_bf16 v[98:101], v[232:235], v[170:173], v[98:101]
	v_mfma_f32_16x16x32_bf16 v[126:129], v[244:247], v[150:153], v[126:129]
	v_mfma_f32_16x16x32_bf16 v[122:125], v[196:199], v[150:153], v[122:125]
	v_mfma_f32_16x16x32_bf16 v[118:121], v[244:247], v[158:161], v[118:121]
	v_mfma_f32_16x16x32_bf16 v[114:117], v[196:199], v[158:161], v[114:117]
	v_mfma_f32_16x16x32_bf16 v[110:113], v[244:247], v[166:169], v[110:113]
	v_mfma_f32_16x16x32_bf16 v[106:109], v[196:199], v[166:169], v[106:109]
	v_mfma_f32_16x16x32_bf16 v[102:105], v[244:247], v[174:177], v[102:105]
	v_mfma_f32_16x16x32_bf16 v[98:101], v[196:199], v[174:177], v[98:101]
	s_setprio 0
	s_add_i32 s8, 0, 0x18000
	v_add_u32_e32 v0, s8, v214
	s_barrier
	ds_read_b128 v[196:199], v0
	ds_read_b128 v[216:219], v0 offset:1024
	ds_read_b128 v[232:235], v0 offset:2048
	ds_read_b128 v[244:247], v0 offset:3072
	s_add_u32 s0, s76, 0x4000
	s_addc_u32 s1, s77, 0
	s_mov_b32 m0, s27
	v_lshl_add_u64 v[130:131], s[0:1], 0, v[178:179]
	ds_read_b128 v[146:149], v215 offset:32768
	ds_read_b128 v[150:153], v215 offset:33792
	ds_read_b128 v[154:157], v215 offset:34816
	ds_read_b128 v[158:161], v215 offset:35840
	ds_read_b128 v[162:165], v215 offset:36864
	ds_read_b128 v[166:169], v215 offset:37888
	ds_read_b128 v[170:173], v215 offset:38912
	ds_read_b128 v[174:177], v215 offset:39936
	global_load_lds_dwordx4 v[130:131], off
	v_lshl_add_u64 v[130:131], s[0:1], 0, v[182:183]
	s_mov_b32 m0, s15
	s_nop 0
	global_load_lds_dwordx4 v[130:131], off
	s_waitcnt lgkmcnt(8)
	s_barrier
	s_waitcnt lgkmcnt(0)
	s_setprio 1
	s_waitcnt lgkmcnt(0)
	v_mfma_f32_16x16x32_bf16 v[2:5], v[196:199], v[146:149], v[2:5]
	v_mfma_f32_16x16x32_bf16 v[30:33], v[232:235], v[146:149], v[30:33]
	v_mfma_f32_16x16x32_bf16 v[26:29], v[196:199], v[154:157], v[26:29]
	v_mfma_f32_16x16x32_bf16 v[22:25], v[232:235], v[154:157], v[22:25]
	v_mfma_f32_16x16x32_bf16 v[18:21], v[196:199], v[162:165], v[18:21]
	v_mfma_f32_16x16x32_bf16 v[14:17], v[232:235], v[162:165], v[14:17]
	v_mfma_f32_16x16x32_bf16 v[10:13], v[196:199], v[170:173], v[10:13]
	v_mfma_f32_16x16x32_bf16 v[6:9], v[232:235], v[170:173], v[6:9]
	v_mfma_f32_16x16x32_bf16 v[2:5], v[216:219], v[150:153], v[2:5]
	v_mfma_f32_16x16x32_bf16 v[30:33], v[244:247], v[150:153], v[30:33]
	v_mfma_f32_16x16x32_bf16 v[26:29], v[216:219], v[158:161], v[26:29]
	v_mfma_f32_16x16x32_bf16 v[22:25], v[244:247], v[158:161], v[22:25]
	v_mfma_f32_16x16x32_bf16 v[18:21], v[216:219], v[166:169], v[18:21]
	v_mfma_f32_16x16x32_bf16 v[14:17], v[244:247], v[166:169], v[14:17]
	v_mfma_f32_16x16x32_bf16 v[10:13], v[216:219], v[174:177], v[10:13]
	v_mfma_f32_16x16x32_bf16 v[6:9], v[244:247], v[174:177], v[6:9]
	s_setprio 0
	s_barrier
	s_add_u32 s0, s74, 0x8000
	v_add_u32_e32 v0, 0, v214
	s_addc_u32 s1, s75, 0
	s_add_i32 s8, s8, s17
	v_add_u32_e32 v0, 0x1c000, v0
	v_lshl_add_u64 v[220:221], s[0:1], 0, v[180:181]
	s_mov_b32 m0, s8
	ds_read_b128 v[130:133], v0
	ds_read_b128 v[134:137], v0 offset:1024
	ds_read_b128 v[138:141], v0 offset:2048
	ds_read_b128 v[142:145], v0 offset:3072
	global_load_lds_dwordx4 v[220:221], off
	v_lshl_add_u64 v[220:221], s[0:1], 0, v[184:185]
	s_add_i32 m0, s8, 0x2000
	s_nop 0
	global_load_lds_dwordx4 v[220:221], off
	s_barrier
; #define PG8_STAGE(bufoff, gbase, voff) do { _Pragma("unroll") for (int _i = 0; _i < 2; ++_i) \
;         __builtin_amdgcn_global_load_lds((const unsigned*)((const char*)(gbase) + (voff)[_i]), (LAS unsigned*)(lds + (bufoff) + ldsw + _i * 8192), 16, 0, 0); } while (0)
; #define PG8_LDA(dst, b, h) do { _Pragma("unroll") for (int m = 0; m < 4; ++m) _Pragma("unroll") for (int k = 0; k < 2; ++k) dst[m][k] = *(const LAS bf16x8*)(lds + PG8_SA(b, h) + aoff + m * 2048 + k * 1024); } while (0)
; #define PG8_MMA(ai, bj, At, Bt) do { __builtin_amdgcn_s_setprio(1); _Pragma("unroll") for (int m = 0; m < 4; ++m) _Pragma("unroll") for (int n = 0; n < 2; ++n) _Pragma("unroll") for (int k = 0; k < 2; ++k) \
;         acc[ai][bj][m][n] = __builtin_amdgcn_mfma_f32_16x16x32_bf16(Bt[n][k], At[m][k], acc[ai][bj][m][n], 0, 0, 0); __builtin_amdgcn_s_setprio(0); } while (0)
; #define PG8_WAIT_L(n) asm volatile("s_waitcnt lgkmcnt(" #n ")" ::: "memory")
; #define PG8_BAR __builtin_amdgcn_s_barrier()
; #define PG8_SCHED __builtin_amdgcn_sched_barrier(0)
; template <class Epi, bool DYN = false>
; __device__ __forceinline__ void gemm_phase(LAS unsigned char* lds, const Gemm g, const Epi& E, int wave, unsigned* ctr = nullptr) {
;     ...
;     auto publish = [&](int si) { if (tid == 0) { int wg = -1;
;             if (ticket < rng_cnt(xcd)) wg = rng_start(xcd) + ticket;
;             else { for (int k = 1; k < 8; ++k) { const int x2 = (xcd + k) & 7; const int t2 = (int)__hip_atomic_fetch_add(ctr + x2 * 16, 1u, __ATOMIC_RELAXED, __HIP_MEMORY_SCOPE_AGENT); if (t2 < rng_cnt(x2)) { wg = rng_start(x2) + t2; break; } } }
;             slot[si] = wg; } };
;     ...
;             PG8_BAR; PG8_WAIT_L(0); PG8_MMA(0, 1, At, B1); PG8_BAR;
;             PG8_LDA(At, 1, 1); PG8_STAGE(PG8_SA(1, 0), a3, voffA);
;             PG8_BAR; PG8_WAIT_L(0); PG8_MMA(1, 0, At, B0); PG8_BAR; PG8_SCHED;
;             if (DYN && t == 0) publish((ui + 1) & 1);
	s_waitcnt lgkmcnt(0)
	s_setprio 1
	s_waitcnt lgkmcnt(0)
	v_mfma_f32_16x16x32_bf16 v[94:97], v[130:133], v[146:149], v[94:97]
	v_mfma_f32_16x16x32_bf16 v[90:93], v[138:141], v[146:149], v[90:93]
	v_mfma_f32_16x16x32_bf16 v[86:89], v[130:133], v[154:157], v[86:89]
	v_mfma_f32_16x16x32_bf16 v[82:85], v[138:141], v[154:157], v[82:85]
	v_mfma_f32_16x16x32_bf16 v[78:81], v[130:133], v[162:165], v[78:81]
	v_mfma_f32_16x16x32_bf16 v[74:77], v[138:141], v[162:165], v[74:77]
	v_mfma_f32_16x16x32_bf16 v[70:73], v[130:133], v[170:173], v[70:73]
	v_mfma_f32_16x16x32_bf16 v[66:69], v[138:141], v[170:173], v[66:69]
	v_mfma_f32_16x16x32_bf16 v[94:97], v[134:137], v[150:153], v[94:97]
	v_mfma_f32_16x16x32_bf16 v[90:93], v[142:145], v[150:153], v[90:93]
	v_mfma_f32_16x16x32_bf16 v[86:89], v[134:137], v[158:161], v[86:89]
	v_mfma_f32_16x16x32_bf16 v[82:85], v[142:145], v[158:161], v[82:85]
	v_mfma_f32_16x16x32_bf16 v[78:81], v[134:137], v[166:169], v[78:81]
	v_mfma_f32_16x16x32_bf16 v[74:77], v[142:145], v[166:169], v[74:77]
	v_mfma_f32_16x16x32_bf16 v[70:73], v[134:137], v[174:177], v[70:73]
	v_mfma_f32_16x16x32_bf16 v[66:69], v[142:145], v[174:177], v[66:69]
	s_setprio 0
	s_mov_b32 m0, s61
	v_lshl_add_u64 v[220:221], s[38:39], 0, v[178:179]
	s_barrier
	ds_read_b128 v[170:173], v215 offset:49152
	ds_read_b128 v[174:177], v215 offset:50176
	ds_read_b128 v[162:165], v215 offset:51200
	ds_read_b128 v[166:169], v215 offset:52224
	ds_read_b128 v[154:157], v215 offset:53248
	ds_read_b128 v[158:161], v215 offset:54272
	ds_read_b128 v[146:149], v215 offset:55296
	ds_read_b128 v[150:153], v215 offset:56320
	global_load_lds_dwordx4 v[220:221], off
	v_lshl_add_u64 v[220:221], s[38:39], 0, v[182:183]
	s_mov_b32 m0, s58
	s_nop 0
	global_load_lds_dwordx4 v[220:221], off
	s_barrier
	s_waitcnt lgkmcnt(0)
	s_setprio 1
	s_waitcnt lgkmcnt(0)
	v_mfma_f32_16x16x32_bf16 v[62:65], v[196:199], v[170:173], v[62:65]
	v_mfma_f32_16x16x32_bf16 v[58:61], v[232:235], v[170:173], v[58:61]
	v_mfma_f32_16x16x32_bf16 v[54:57], v[196:199], v[162:165], v[54:57]
	v_mfma_f32_16x16x32_bf16 v[50:53], v[232:235], v[162:165], v[50:53]
	v_mfma_f32_16x16x32_bf16 v[46:49], v[196:199], v[154:157], v[46:49]
	v_mfma_f32_16x16x32_bf16 v[42:45], v[232:235], v[154:157], v[42:45]
	v_mfma_f32_16x16x32_bf16 v[38:41], v[196:199], v[146:149], v[38:41]
	v_mfma_f32_16x16x32_bf16 v[34:37], v[232:235], v[146:149], v[34:37]
	v_mfma_f32_16x16x32_bf16 v[62:65], v[216:219], v[174:177], v[62:65]
	v_mfma_f32_16x16x32_bf16 v[58:61], v[244:247], v[174:177], v[58:61]
	v_mfma_f32_16x16x32_bf16 v[54:57], v[216:219], v[166:169], v[54:57]
	v_mfma_f32_16x16x32_bf16 v[50:53], v[244:247], v[166:169], v[50:53]
	v_mfma_f32_16x16x32_bf16 v[46:49], v[216:219], v[158:161], v[46:49]
	v_mfma_f32_16x16x32_bf16 v[42:45], v[244:247], v[158:161], v[42:45]
	v_mfma_f32_16x16x32_bf16 v[38:41], v[216:219], v[150:153], v[38:41]
	v_mfma_f32_16x16x32_bf16 v[34:37], v[244:247], v[150:153], v[34:37]
	s_setprio 0
	s_barrier
	v_or_b32_e32 v0, s7, v202
	v_cmp_eq_u32_e64 s[38:39], 0, v0
	s_and_saveexec_b64 s[76:77], s[38:39]
	s_cbranch_execz .LBB0_919
	v_cmp_lt_i32_e32 vcc, 0x20f, v203
	v_add_u32_e32 v0, s90, v203
	s_and_saveexec_b64 s[78:79], vcc
	s_cbranch_execz .LBB0_918
	v_readlane_b32 s0, v254, 11
	s_nop 1
	v_mov_b32_e32 v196, s0
	ds_read_b32 v196, v196
	v_mov_b32_e32 v0, -1
	s_waitcnt lgkmcnt(0)
	v_readfirstlane_b32 s0, v196
	s_cmp_eq_u32 s0, 8
	s_cbranch_scc1 .LBB0_918
	v_mov_b64_e32 v[196:197], s[40:41]
	s_waitcnt vmcnt(0)
	flat_atomic_add v0, v[196:197], v224 sc0
	s_movk_i32 s0, 0x20f
	s_waitcnt vmcnt(0) lgkmcnt(0)
	v_cmp_lt_i32_e64 s[38:39], s0, v0
	v_add_u32_e32 v0, s63, v0
	s_and_saveexec_b64 s[0:1], s[38:39]
	s_cbranch_execz .LBB0_917
	v_mov_b64_e32 v[196:197], s[42:43]
	flat_atomic_add v0, v[196:197], v224 sc0
	s_movk_i32 s8, 0x20f
	s_waitcnt vmcnt(0) lgkmcnt(0)
	v_cmp_lt_i32_e64 s[38:39], s8, v0
	v_add_u32_e32 v0, s2, v0
	s_and_saveexec_b64 s[80:81], s[38:39]
	s_cbranch_execz .LBB0_916
	v_mov_b64_e32 v[196:197], s[44:45]
	flat_atomic_add v0, v[196:197], v224 sc0
	s_waitcnt vmcnt(0) lgkmcnt(0)
	v_cmp_lt_i32_e64 s[38:39], s8, v0
	v_add_u32_e32 v0, s3, v0
	s_and_saveexec_b64 s[82:83], s[38:39]
	s_cbranch_execz .LBB0_915
	v_mov_b64_e32 v[196:197], s[50:51]
	flat_atomic_add v0, v[196:197], v224 sc0
	s_waitcnt vmcnt(0) lgkmcnt(0)
	v_cmp_lt_i32_e64 s[38:39], s8, v0
	v_add_u32_e32 v0, s95, v0
	s_and_saveexec_b64 s[84:85], s[38:39]
	s_cbranch_execz .LBB0_914
	v_mov_b64_e32 v[196:197], s[54:55]
	flat_atomic_add v0, v[196:197], v224 sc0
	s_waitcnt vmcnt(0) lgkmcnt(0)
	v_cmp_lt_i32_e64 s[38:39], s8, v0
	v_add_u32_e32 v0, s28, v0
	s_and_saveexec_b64 s[86:87], s[38:39]
	s_cbranch_execz .LBB0_913
	v_readlane_b32 s8, v254, 54
	v_readlane_b32 s9, v254, 55
	s_nop 1
	v_mov_b64_e32 v[196:197], s[8:9]
	flat_atomic_add v0, v[196:197], v224 sc0
	s_movk_i32 s8, 0x20f
	s_waitcnt vmcnt(0) lgkmcnt(0)
	v_cmp_lt_i32_e64 s[38:39], s8, v0
	v_readlane_b32 s8, v254, 39
	s_nop 1
	v_add_u32_e32 v0, s8, v0
	s_and_saveexec_b64 s[88:89], s[38:39]
	s_cbranch_execz .LBB0_912
	v_readlane_b32 s8, v254, 56
	v_readlane_b32 s9, v254, 57
	s_nop 1
	v_mov_b64_e32 v[196:197], s[8:9]
	flat_atomic_add v0, v[196:197], v224 sc0
	v_readlane_b32 s8, v254, 43
	s_waitcnt vmcnt(0) lgkmcnt(0)
	v_cmp_gt_i32_e64 s[38:39], s91, v0
	v_add_u32_e32 v191, s8, v0
	s_nop 0
	v_cndmask_b32_e64 v0, -1, v191, s[38:39]
	s_branch .LBB0_912
